# static s_setprio 1 for waves 4-7 around the K-loops of phases 3, 10, 12, 13; per-segment flips deleted
# speedup vs baseline: 1.0138x; 1.0058x over previous
; template <class Epi, class Sched>
; __device__ __forceinline__ void gemm_phase(LAS unsigned char* lds, const Gemm g, const Sched& S, const Epi& E) {
;     ...
;         for (int a = 0; a < 2; ++a)
; #pragma unroll
;             for (int b = 0; b < 2; ++b)
; #pragma unroll
;                 for (int m = 0; m < 4; ++m)
; #pragma unroll
;                     for (int n = 0; n < 2; ++n) acc[a][b][m][n] = (f32x4){0.f, 0.f, 0.f, 0.f};
;         cur = nxt; cA = nA; cB = nB; ++ui;
.LBB0_1652:
	s_mov_b32 s80, s79
	s_add_i32 s65, s65, 1
	s_mov_b32 s68, s12
	s_mul_i32 s12, s65, s96
	s_add_i32 s35, s12, s2
	s_bfe_u32 s79, s35, 0x40003
	s_lshl_b32 s79, s79, 8
	s_cmpk_lt_u32 s35, 0x100
	s_cselect_b32 s79, s79, 0
	s_mov_b32 s69, s14
	s_max_i32 s14, s35, 0x100
	s_and_b32 s66, s14, 7
	s_lshl_b32 s15, s66, 9
	s_cmpk_lt_i32 s35, 0x100
	s_cselect_b64 s[12:13], -1, 0
	s_and_b64 s[12:13], s[12:13], exec
	s_cselect_b32 s12, s35, 0
	s_cselect_b32 s70, 0, s15
	s_ashr_i32 s13, s12, 31
	s_lshr_b32 s13, s13, 29
	s_add_i32 s13, s12, s13
	s_ashr_i32 s15, s13, 3
	s_and_b32 s13, s13, 0x7fffff8
	s_sub_i32 s12, s12, s13
	s_lshl_b32 s12, s12, 5
	s_add_i32 s12, s12, s15
	s_ashr_i32 s13, s12, 31
	s_lshr_b32 s13, s13, 26
	s_add_i32 s15, s12, s13
	s_and_b32 s13, s15, 0xffffffc0
	s_mov_b64 s[36:37], s[18:19]
	s_sub_i32 s18, s12, s13
	s_bfe_i32 s12, s18, 0x80000
	s_bfe_u32 s12, s12, 0x3000c
	s_add_i32 s19, s18, s12
	s_bfe_i32 s12, s19, 0x80000
	s_sext_i32_i16 s12, s12
	s_mov_b64 s[6:7], s[20:21]
	s_ashr_i32 s20, s12, 3
	s_bfe_u32 s21, s14, 0x30003
	s_cmpk_lt_i32 s35, 0x100
	s_cselect_b64 s[12:13], -1, 0
	s_and_b64 s[12:13], s[12:13], exec
	s_cselect_b32 s12, s20, s21
	s_ashr_i32 s13, s15, 6
	s_and_b32 s15, s19, 0xf8
	s_sub_i32 s15, s18, s15
	s_addk_i32 s14, 0xff00
	s_lshl_b32 s13, s13, 3
	s_sext_i32_i8 s15, s15
	s_lshr_b32 s14, s14, 6
	s_add_i32 s13, s13, s15
	s_add_i32 s18, s14, 32
	s_cmpk_lt_i32 s35, 0x100
	s_cselect_b64 s[28:29], -1, 0
	s_and_b64 s[14:15], s[28:29], exec
	s_cselect_b32 s14, s13, s18
	s_cmpk_gt_i32 s35, 0x17f
	s_cselect_b64 s[30:31], -1, 0
	s_ashr_i32 s15, s14, 31
	s_lshl_b64 s[18:19], s[14:15], 20
	s_add_u32 s13, s38, s18
	s_addc_u32 s15, s39, s19
	s_add_u32 s20, s13, s70
	s_addc_u32 s21, s15, 0
	s_ashr_i32 s13, s12, 31
	s_lshl_b64 s[18:19], s[12:13], 20
	s_add_u32 s13, s40, s18
	s_addc_u32 s15, s41, s19
	s_add_u32 s18, s13, s70
	s_addc_u32 s19, s15, 0
	s_cmpk_lt_i32 s35, 0x180
	s_cselect_b32 s13, s21, s7
	s_cselect_b32 s15, s20, s6
	s_cselect_b32 s70, s19, s37
	s_cselect_b32 s71, s18, s36
	s_add_i32 s72, s67, -2
	s_add_u32 s6, s6, 0x80080
	s_addc_u32 s7, s7, 0
	s_add_u32 s73, s36, 0x100
	v_mov_b32_e32 v0, 0
	s_mov_b32 s34, 0
	s_addc_u32 s74, s37, 0
	v_mov_b32_e32 v1, v0
	v_mov_b32_e32 v2, v0
	v_mov_b32_e32 v3, v0
	v_mov_b32_e32 v4, v0
	v_mov_b32_e32 v5, v0
	v_mov_b32_e32 v6, v0
	v_mov_b32_e32 v7, v0
	v_mov_b32_e32 v8, v0
	v_mov_b32_e32 v9, v0
	v_mov_b32_e32 v10, v0
	v_mov_b32_e32 v11, v0
	v_mov_b32_e32 v12, v0
	v_mov_b32_e32 v13, v0
	v_mov_b32_e32 v14, v0
	v_mov_b32_e32 v15, v0
	v_mov_b32_e32 v20, v0
	v_mov_b32_e32 v21, v0
	v_mov_b32_e32 v22, v0
	v_mov_b32_e32 v23, v0
	v_mov_b32_e32 v28, v0
	v_mov_b32_e32 v29, v0
	v_mov_b32_e32 v30, v0
	v_mov_b32_e32 v31, v0
	v_mov_b32_e32 v36, v0
	v_mov_b32_e32 v37, v0
	v_mov_b32_e32 v38, v0
	v_mov_b32_e32 v39, v0
	v_mov_b32_e32 v44, v0
	v_mov_b32_e32 v45, v0
	v_mov_b32_e32 v46, v0
	v_mov_b32_e32 v47, v0
	v_mov_b32_e32 v16, v0
	v_mov_b32_e32 v17, v0
	v_mov_b32_e32 v18, v0
	v_mov_b32_e32 v19, v0
	v_mov_b32_e32 v24, v0
	v_mov_b32_e32 v25, v0
	v_mov_b32_e32 v26, v0
	v_mov_b32_e32 v27, v0
	v_mov_b32_e32 v32, v0
	v_mov_b32_e32 v33, v0
	v_mov_b32_e32 v34, v0
	v_mov_b32_e32 v35, v0
	v_mov_b32_e32 v40, v0
	v_mov_b32_e32 v41, v0
	v_mov_b32_e32 v42, v0
	v_mov_b32_e32 v43, v0
	v_mov_b32_e32 v48, v0
	v_mov_b32_e32 v49, v0
	v_mov_b32_e32 v50, v0
	v_mov_b32_e32 v51, v0
	v_mov_b32_e32 v52, v0
	v_mov_b32_e32 v53, v0
	v_mov_b32_e32 v54, v0
	v_mov_b32_e32 v55, v0
	v_mov_b32_e32 v56, v0
	v_mov_b32_e32 v57, v0
	v_mov_b32_e32 v58, v0
	v_mov_b32_e32 v59, v0
	v_mov_b32_e32 v60, v0
	v_mov_b32_e32 v61, v0
	v_mov_b32_e32 v62, v0
	v_mov_b32_e32 v63, v0
	v_mov_b32_e32 v64, v0
	v_mov_b32_e32 v65, v0
	v_mov_b32_e32 v66, v0
	v_mov_b32_e32 v67, v0
	v_mov_b32_e32 v68, v0
	v_mov_b32_e32 v69, v0
	v_mov_b32_e32 v70, v0
	v_mov_b32_e32 v71, v0
	v_mov_b32_e32 v72, v0
	v_mov_b32_e32 v73, v0
	v_mov_b32_e32 v74, v0
	v_mov_b32_e32 v75, v0
	v_mov_b32_e32 v76, v0
	v_mov_b32_e32 v77, v0
	v_mov_b32_e32 v78, v0
	v_mov_b32_e32 v79, v0
	v_mov_b32_e32 v84, v0
	v_mov_b32_e32 v85, v0
	v_mov_b32_e32 v86, v0
	v_mov_b32_e32 v87, v0
	v_mov_b32_e32 v92, v0
	v_mov_b32_e32 v93, v0
	v_mov_b32_e32 v94, v0
	v_mov_b32_e32 v95, v0
	v_mov_b32_e32 v100, v0
	v_mov_b32_e32 v101, v0
	v_mov_b32_e32 v102, v0
	v_mov_b32_e32 v103, v0
	v_mov_b32_e32 v108, v0
	v_mov_b32_e32 v109, v0
	v_mov_b32_e32 v110, v0
	v_mov_b32_e32 v111, v0
	v_mov_b32_e32 v80, v0
	v_mov_b32_e32 v81, v0
	v_mov_b32_e32 v82, v0
	v_mov_b32_e32 v83, v0
	v_mov_b32_e32 v88, v0
	v_mov_b32_e32 v89, v0
	v_mov_b32_e32 v90, v0
	v_mov_b32_e32 v91, v0
	v_mov_b32_e32 v96, v0
	v_mov_b32_e32 v97, v0
	v_mov_b32_e32 v98, v0
	v_mov_b32_e32 v99, v0
	v_mov_b32_e32 v104, v0
	v_mov_b32_e32 v105, v0
	v_mov_b32_e32 v106, v0
	v_mov_b32_e32 v107, v0
	v_mov_b32_e32 v112, v0
	v_mov_b32_e32 v113, v0
	v_mov_b32_e32 v114, v0
	v_mov_b32_e32 v115, v0
	v_mov_b32_e32 v116, v0
	v_mov_b32_e32 v117, v0
	v_mov_b32_e32 v118, v0
	v_mov_b32_e32 v119, v0
	v_mov_b32_e32 v120, v0
	v_mov_b32_e32 v121, v0
	v_mov_b32_e32 v122, v0
	v_mov_b32_e32 v123, v0
	v_mov_b32_e32 v124, v0
	v_mov_b32_e32 v125, v0
	v_mov_b32_e32 v126, v0
	v_mov_b32_e32 v127, v0
	s_lshr_b32 s92, s3, 8
	s_cmp_lg_u32 s92, 0
	s_cbranch_scc0 .Lprio_1653
	s_setprio 1
; #define PG8_STAGE(bufoff, gbase, voff) do { _Pragma("unroll") for (int _i = 0; _i < 2; ++_i) \
;         __builtin_amdgcn_global_load_lds((const unsigned*)((const char*)(gbase) + (voff)[_i]), (LAS unsigned*)(lds + (bufoff) + ldsw + _i * 8192), 16, 0, 0); } while (0)
; #define PG8_LDA(dst, b, h) do { _Pragma("unroll") for (int m = 0; m < 4; ++m) _Pragma("unroll") for (int k = 0; k < 2; ++k) dst[m][k] = *(const LAS bf16x8*)(lds + PG8_SA(b, h) + aoff + m * 2048 + k * 1024); } while (0)
; #define PG8_LDB(dst, b, h) do { _Pragma("unroll") for (int n = 0; n < 2; ++n) _Pragma("unroll") for (int k = 0; k < 2; ++k) dst[n][k] = *(const LAS bf16x8*)(lds + PG8_SB(b, h) + boff + n * 2048 + k * 1024); } while (0)
; #define PG8_MMA(ai, bj, At, Bt) do { __builtin_amdgcn_s_setprio(1); _Pragma("unroll") for (int m = 0; m < 4; ++m) _Pragma("unroll") for (int n = 0; n < 2; ++n) _Pragma("unroll") for (int k = 0; k < 2; ++k) \
;         acc[ai][bj][m][n] = __builtin_amdgcn_mfma_f32_16x16x32_bf16(Bt[n][k], At[m][k], acc[ai][bj][m][n], 0, 0, 0); __builtin_amdgcn_s_setprio(0); } while (0)
; #define PG8_WAIT_L(n) asm volatile("s_waitcnt lgkmcnt(" #n ")" ::: "memory")
; #define PG8_BAR __builtin_amdgcn_s_barrier()
; #define PG8_SCHED __builtin_amdgcn_sched_barrier(0)
; template <class Epi, class Sched>
; __device__ __forceinline__ void gemm_phase(LAS unsigned char* lds, const Gemm g, const Sched& S, const Epi& E) {
;     ...
;         for (int t = 0; t < nt; t += 2) {
;             const bool last = (t == nt - 2);
;             const char* a1 = cA + (size_t)(t + 1) * kstep;
;             const char* a2 = last ? nA : cA + (size_t)(t + 2) * kstep; const char* b2 = last ? nB : cB + (size_t)(t + 2) * kstep;
;             const char* a3 = a2 + kstep; const char* b3 = b2 + kstep;
;             PG8_LDB(B0, 0, 0); PG8_SCHED; PG8_LDA(At, 0, 0); PG8_STAGE(PG8_SA(1, 1), a1 + hstepA, voffA);
;             PG8_WAIT_L(8); PG8_BAR; PG8_WAIT_L(0); PG8_MMA(0, 0, At, B0); PG8_BAR; PG8_SCHED;
;             PG8_LDB(B1, 0, 1); PG8_STAGE(PG8_SB(0, 0), b2, voffB);
;             PG8_BAR; PG8_WAIT_L(0); if constexpr (!Epi::DIAG) PG8_MMA(0, 1, At, B1); PG8_BAR;
;             PG8_LDA(At, 0, 1); PG8_STAGE(PG8_SA(0, 0), a2, voffA);
;             PG8_BAR; PG8_WAIT_L(0); if constexpr (!Epi::DIAG) PG8_MMA(1, 0, At, B0); PG8_BAR; PG8_SCHED;
.Lprio_1653:
.LBB0_1653:
	ds_read_b128 v[138:141], v155
	ds_read_b128 v[142:145], v155 offset:1024
	ds_read_b128 v[146:149], v155 offset:2048
	ds_read_b128 v[162:165], v155 offset:3072
	s_add_i32 s75, s34, 2
	s_add_u32 s81, s80, 0x100
	s_and_b32 s81, s81, 0xfff
	s_add_u32 s35, s6, s81
	s_addc_u32 s36, s7, 0
	s_sub_u32 s35, s35, 0x80080
	s_subb_u32 s36, s36, 0
	s_add_u32 s88, s15, s79
	s_addc_u32 s89, s13, 0
	s_cmp_eq_u32 s72, s34
	s_cselect_b32 s37, s89, s36
	s_cselect_b32 s36, s88, s35
	s_add_u32 s88, s73, s81
	s_addc_u32 s89, s74, 0
	s_sub_u32 s88, s88, 0x100
	s_subb_u32 s89, s89, 0
	s_add_u32 s90, s71, s79
	s_addc_u32 s91, s70, 0
	s_cmp_eq_u32 s72, s34
	s_cselect_b32 s35, s91, s89
	s_cselect_b32 s34, s90, s88
	s_add_u32 s88, s6, s80
	s_addc_u32 s89, s7, 0
	v_lshl_add_u64 v[150:151], s[88:89], 0, v[134:135]
	s_add_i32 m0, s43, 0xc000
	ds_read_b128 v[166:169], v156
	ds_read_b128 v[170:173], v156 offset:1024
	ds_read_b128 v[174:177], v156 offset:2048
	ds_read_b128 v[178:181], v156 offset:3072
	ds_read_b128 v[186:189], v156 offset:4096
	ds_read_b128 v[190:193], v156 offset:5120
	ds_read_b128 v[194:197], v156 offset:6144
	ds_read_b128 v[198:201], v156 offset:7168
	global_load_lds_dwordx4 v[150:151], off
	v_lshl_add_u64 v[150:151], s[88:89], 0, v[136:137]
	s_add_i32 m0, s43, 0xe000
	s_nop 0
	global_load_lds_dwordx4 v[150:151], off
	s_waitcnt lgkmcnt(8)
	s_barrier
	s_waitcnt lgkmcnt(0)
	s_waitcnt lgkmcnt(0)
	v_mfma_f32_16x16x32_bf16 v[124:127], v[138:141], v[166:169], v[124:127]
	v_mfma_f32_16x16x32_bf16 v[120:123], v[146:149], v[166:169], v[120:123]
	v_mfma_f32_16x16x32_bf16 v[116:119], v[138:141], v[174:177], v[116:119]
	v_mfma_f32_16x16x32_bf16 v[112:115], v[146:149], v[174:177], v[112:115]
	v_mfma_f32_16x16x32_bf16 v[104:107], v[138:141], v[186:189], v[104:107]
	v_mfma_f32_16x16x32_bf16 v[96:99], v[146:149], v[186:189], v[96:99]
	v_mfma_f32_16x16x32_bf16 v[88:91], v[138:141], v[194:197], v[88:91]
	v_mfma_f32_16x16x32_bf16 v[80:83], v[146:149], v[194:197], v[80:83]
	v_mfma_f32_16x16x32_bf16 v[124:127], v[142:145], v[170:173], v[124:127]
	v_mfma_f32_16x16x32_bf16 v[120:123], v[162:165], v[170:173], v[120:123]
	v_mfma_f32_16x16x32_bf16 v[116:119], v[142:145], v[178:181], v[116:119]
	v_mfma_f32_16x16x32_bf16 v[112:115], v[162:165], v[178:181], v[112:115]
	v_mfma_f32_16x16x32_bf16 v[104:107], v[142:145], v[190:193], v[104:107]
	v_mfma_f32_16x16x32_bf16 v[96:99], v[162:165], v[190:193], v[96:99]
	v_mfma_f32_16x16x32_bf16 v[88:91], v[142:145], v[198:201], v[88:91]
	v_mfma_f32_16x16x32_bf16 v[80:83], v[162:165], v[198:201], v[80:83]
	s_barrier
	s_add_i32 s76, s53, s42
	v_lshl_add_u64 v[150:151], s[34:35], 0, v[128:129]
	s_mov_b32 m0, s76
	ds_read_b128 v[202:205], v157
	ds_read_b128 v[206:209], v157 offset:1024
	ds_read_b128 v[210:213], v157 offset:2048
	ds_read_b128 v[214:217], v157 offset:3072
	global_load_lds_dwordx4 v[150:151], off
	v_lshl_add_u64 v[158:159], s[34:35], 0, v[130:131]
	s_add_i32 m0, s76, 0x2000
	s_nop 0
	global_load_lds_dwordx4 v[158:159], off
	s_barrier
	s_waitcnt lgkmcnt(0)
	s_waitcnt lgkmcnt(0)
	v_mfma_f32_16x16x32_bf16 v[108:111], v[202:205], v[166:169], v[108:111]
	v_mfma_f32_16x16x32_bf16 v[100:103], v[210:213], v[166:169], v[100:103]
	v_mfma_f32_16x16x32_bf16 v[92:95], v[202:205], v[174:177], v[92:95]
	v_mfma_f32_16x16x32_bf16 v[84:87], v[210:213], v[174:177], v[84:87]
	v_mfma_f32_16x16x32_bf16 v[76:79], v[202:205], v[186:189], v[76:79]
	v_mfma_f32_16x16x32_bf16 v[72:75], v[210:213], v[186:189], v[72:75]
	v_mfma_f32_16x16x32_bf16 v[68:71], v[202:205], v[194:197], v[68:71]
	v_mfma_f32_16x16x32_bf16 v[64:67], v[210:213], v[194:197], v[64:67]
	v_mfma_f32_16x16x32_bf16 v[108:111], v[206:209], v[170:173], v[108:111]
	v_mfma_f32_16x16x32_bf16 v[100:103], v[214:217], v[170:173], v[100:103]
	v_mfma_f32_16x16x32_bf16 v[92:95], v[206:209], v[178:181], v[92:95]
	v_mfma_f32_16x16x32_bf16 v[84:87], v[214:217], v[178:181], v[84:87]
	v_mfma_f32_16x16x32_bf16 v[76:79], v[206:209], v[190:193], v[76:79]
	v_mfma_f32_16x16x32_bf16 v[72:75], v[214:217], v[190:193], v[72:75]
	v_mfma_f32_16x16x32_bf16 v[68:71], v[206:209], v[198:201], v[68:71]
	v_mfma_f32_16x16x32_bf16 v[64:67], v[214:217], v[198:201], v[64:67]
	s_mov_b32 m0, s43
	v_lshl_add_u64 v[182:183], s[36:37], 0, v[128:129]
	s_barrier
	ds_read_b128 v[166:169], v156 offset:16384
	ds_read_b128 v[170:173], v156 offset:17408
	ds_read_b128 v[174:177], v156 offset:18432
	ds_read_b128 v[178:181], v156 offset:19456
	ds_read_b128 v[186:189], v156 offset:20480
	ds_read_b128 v[190:193], v156 offset:21504
	ds_read_b128 v[194:197], v156 offset:22528
	ds_read_b128 v[198:201], v156 offset:23552
	global_load_lds_dwordx4 v[182:183], off
	v_lshl_add_u64 v[218:219], s[36:37], 0, v[130:131]
	s_mov_b32 m0, s44
	s_nop 0
	global_load_lds_dwordx4 v[218:219], off
	s_barrier
	s_waitcnt lgkmcnt(0)
	s_waitcnt lgkmcnt(0)
	v_mfma_f32_16x16x32_bf16 v[60:63], v[138:141], v[166:169], v[60:63]
	v_mfma_f32_16x16x32_bf16 v[56:59], v[146:149], v[166:169], v[56:59]
	v_mfma_f32_16x16x32_bf16 v[52:55], v[138:141], v[174:177], v[52:55]
	v_mfma_f32_16x16x32_bf16 v[48:51], v[146:149], v[174:177], v[48:51]
	v_mfma_f32_16x16x32_bf16 v[40:43], v[138:141], v[186:189], v[40:43]
	v_mfma_f32_16x16x32_bf16 v[32:35], v[146:149], v[186:189], v[32:35]
	v_mfma_f32_16x16x32_bf16 v[24:27], v[138:141], v[194:197], v[24:27]
	v_mfma_f32_16x16x32_bf16 v[16:19], v[146:149], v[194:197], v[16:19]
	v_mfma_f32_16x16x32_bf16 v[60:63], v[142:145], v[170:173], v[60:63]
	v_mfma_f32_16x16x32_bf16 v[56:59], v[162:165], v[170:173], v[56:59]
	v_mfma_f32_16x16x32_bf16 v[52:55], v[142:145], v[178:181], v[52:55]
	v_mfma_f32_16x16x32_bf16 v[48:51], v[162:165], v[178:181], v[48:51]
	v_mfma_f32_16x16x32_bf16 v[40:43], v[142:145], v[190:193], v[40:43]
	v_mfma_f32_16x16x32_bf16 v[32:35], v[162:165], v[190:193], v[32:35]
	v_mfma_f32_16x16x32_bf16 v[24:27], v[142:145], v[198:201], v[24:27]
	v_mfma_f32_16x16x32_bf16 v[16:19], v[162:165], v[198:201], v[16:19]
	s_barrier
; #define PG8_STAGE(bufoff, gbase, voff) do { _Pragma("unroll") for (int _i = 0; _i < 2; ++_i) \
;         __builtin_amdgcn_global_load_lds((const unsigned*)((const char*)(gbase) + (voff)[_i]), (LAS unsigned*)(lds + (bufoff) + ldsw + _i * 8192), 16, 0, 0); } while (0)
; #define PG8_LDA(dst, b, h) do { _Pragma("unroll") for (int m = 0; m < 4; ++m) _Pragma("unroll") for (int k = 0; k < 2; ++k) dst[m][k] = *(const LAS bf16x8*)(lds + PG8_SA(b, h) + aoff + m * 2048 + k * 1024); } while (0)
; #define PG8_LDB(dst, b, h) do { _Pragma("unroll") for (int n = 0; n < 2; ++n) _Pragma("unroll") for (int k = 0; k < 2; ++k) dst[n][k] = *(const LAS bf16x8*)(lds + PG8_SB(b, h) + boff + n * 2048 + k * 1024); } while (0)
; #define PG8_MMA(ai, bj, At, Bt) do { __builtin_amdgcn_s_setprio(1); _Pragma("unroll") for (int m = 0; m < 4; ++m) _Pragma("unroll") for (int n = 0; n < 2; ++n) _Pragma("unroll") for (int k = 0; k < 2; ++k) \
;         acc[ai][bj][m][n] = __builtin_amdgcn_mfma_f32_16x16x32_bf16(Bt[n][k], At[m][k], acc[ai][bj][m][n], 0, 0, 0); __builtin_amdgcn_s_setprio(0); } while (0)
; #define PG8_WAIT_V(n) asm volatile("s_waitcnt vmcnt(" #n ")" ::: "memory")
; #define PG8_WAIT_L(n) asm volatile("s_waitcnt lgkmcnt(" #n ")" ::: "memory")
; #define PG8_BAR __builtin_amdgcn_s_barrier()
; #define PG8_SCHED __builtin_amdgcn_sched_barrier(0)
; template <class Epi, class Sched>
; __device__ __forceinline__ void gemm_phase(LAS unsigned char* lds, const Gemm g, const Sched& S, const Epi& E) {
;     ...
;             PG8_STAGE(PG8_SB(0, 1), b2 + hstepB, voffB);
;             PG8_WAIT_V(6); PG8_BAR; PG8_MMA(1, 1, At, B1); PG8_BAR;
;             PG8_LDB(B0, 1, 0); PG8_SCHED; PG8_LDA(At, 1, 0); PG8_STAGE(PG8_SA(0, 1), a2 + hstepA, voffA);
;             PG8_WAIT_L(8); PG8_BAR; PG8_WAIT_L(0); PG8_MMA(0, 0, At, B0); PG8_BAR; PG8_SCHED;
;             PG8_LDB(B1, 1, 1); PG8_STAGE(PG8_SB(1, 0), b3, voffB);
;             PG8_BAR; PG8_WAIT_L(0); if constexpr (!Epi::DIAG) PG8_MMA(0, 1, At, B1); PG8_BAR;
;             PG8_LDA(At, 1, 1); PG8_STAGE(PG8_SA(1, 0), a3, voffA);
	s_add_u32 s76, s34, 0x80000
	s_addc_u32 s77, s35, 0
	s_add_i32 s78, s55, s42
	v_lshl_add_u64 v[138:139], s[76:77], 0, v[128:129]
	s_mov_b32 m0, s78
	s_nop 0
	global_load_lds_dwordx4 v[138:139], off
	v_lshl_add_u64 v[138:139], s[76:77], 0, v[130:131]
	s_add_i32 m0, s78, 0x2000
	s_nop 0
	global_load_lds_dwordx4 v[138:139], off
	s_waitcnt vmcnt(6)
	s_barrier
	v_mfma_f32_16x16x32_bf16 v[44:47], v[202:205], v[166:169], v[44:47]
	v_mfma_f32_16x16x32_bf16 v[36:39], v[210:213], v[166:169], v[36:39]
	v_mfma_f32_16x16x32_bf16 v[28:31], v[202:205], v[174:177], v[28:31]
	v_mfma_f32_16x16x32_bf16 v[20:23], v[210:213], v[174:177], v[20:23]
	v_mfma_f32_16x16x32_bf16 v[12:15], v[202:205], v[186:189], v[12:15]
	v_mfma_f32_16x16x32_bf16 v[8:11], v[210:213], v[186:189], v[8:11]
	v_mfma_f32_16x16x32_bf16 v[4:7], v[202:205], v[194:197], v[4:7]
	v_mfma_f32_16x16x32_bf16 v[0:3], v[210:213], v[194:197], v[0:3]
	v_mfma_f32_16x16x32_bf16 v[44:47], v[206:209], v[170:173], v[44:47]
	v_mfma_f32_16x16x32_bf16 v[36:39], v[214:217], v[170:173], v[36:39]
	v_mfma_f32_16x16x32_bf16 v[28:31], v[206:209], v[178:181], v[28:31]
	v_mfma_f32_16x16x32_bf16 v[20:23], v[214:217], v[178:181], v[20:23]
	v_mfma_f32_16x16x32_bf16 v[12:15], v[206:209], v[190:193], v[12:15]
	v_mfma_f32_16x16x32_bf16 v[8:11], v[214:217], v[190:193], v[8:11]
	v_mfma_f32_16x16x32_bf16 v[4:7], v[206:209], v[198:201], v[4:7]
	v_mfma_f32_16x16x32_bf16 v[0:3], v[214:217], v[198:201], v[0:3]
	s_add_i32 s76, 0, 0x18000
	v_add_u32_e32 v132, s76, v153
	s_barrier
	ds_read_b128 v[138:141], v132
	ds_read_b128 v[142:145], v132 offset:1024
	ds_read_b128 v[146:149], v132 offset:2048
	ds_read_b128 v[162:165], v132 offset:3072
	s_add_u32 s36, s36, 0x80000
	s_addc_u32 s37, s37, 0
	s_mov_b32 m0, s45
	v_lshl_add_u64 v[202:203], s[36:37], 0, v[128:129]
	ds_read_b128 v[166:169], v156 offset:32768
	ds_read_b128 v[170:173], v156 offset:33792
	ds_read_b128 v[174:177], v156 offset:34816
	ds_read_b128 v[178:181], v156 offset:35840
	ds_read_b128 v[186:189], v156 offset:36864
	ds_read_b128 v[190:193], v156 offset:37888
	ds_read_b128 v[194:197], v156 offset:38912
	ds_read_b128 v[198:201], v156 offset:39936
	global_load_lds_dwordx4 v[202:203], off
	v_lshl_add_u64 v[202:203], s[36:37], 0, v[130:131]
	s_mov_b32 m0, s46
	s_nop 0
	global_load_lds_dwordx4 v[202:203], off
	s_waitcnt lgkmcnt(8)
	s_barrier
	s_waitcnt lgkmcnt(0)
	s_waitcnt lgkmcnt(0)
	v_mfma_f32_16x16x32_bf16 v[124:127], v[138:141], v[166:169], v[124:127]
	v_mfma_f32_16x16x32_bf16 v[120:123], v[146:149], v[166:169], v[120:123]
	v_mfma_f32_16x16x32_bf16 v[116:119], v[138:141], v[174:177], v[116:119]
	v_mfma_f32_16x16x32_bf16 v[112:115], v[146:149], v[174:177], v[112:115]
	v_mfma_f32_16x16x32_bf16 v[104:107], v[138:141], v[186:189], v[104:107]
	v_mfma_f32_16x16x32_bf16 v[96:99], v[146:149], v[186:189], v[96:99]
	v_mfma_f32_16x16x32_bf16 v[88:91], v[138:141], v[194:197], v[88:91]
	v_mfma_f32_16x16x32_bf16 v[80:83], v[146:149], v[194:197], v[80:83]
	v_mfma_f32_16x16x32_bf16 v[124:127], v[142:145], v[170:173], v[124:127]
	v_mfma_f32_16x16x32_bf16 v[120:123], v[162:165], v[170:173], v[120:123]
	v_mfma_f32_16x16x32_bf16 v[116:119], v[142:145], v[178:181], v[116:119]
	v_mfma_f32_16x16x32_bf16 v[112:115], v[162:165], v[178:181], v[112:115]
	v_mfma_f32_16x16x32_bf16 v[104:107], v[142:145], v[190:193], v[104:107]
	v_mfma_f32_16x16x32_bf16 v[96:99], v[162:165], v[190:193], v[96:99]
	v_mfma_f32_16x16x32_bf16 v[88:91], v[142:145], v[198:201], v[88:91]
	v_mfma_f32_16x16x32_bf16 v[80:83], v[162:165], v[198:201], v[80:83]
	s_barrier
	s_add_i32 s36, 0, 0x1c000
	s_add_i32 s37, s76, s42
	v_add_u32_e32 v132, s36, v153
	v_lshl_add_u64 v[150:151], v[150:151], 0, s[24:25]
	s_mov_b32 m0, s37
	ds_read_b128 v[202:205], v132
	ds_read_b128 v[206:209], v132 offset:1024
	ds_read_b128 v[210:213], v132 offset:2048
	ds_read_b128 v[214:217], v132 offset:3072
	global_load_lds_dwordx4 v[150:151], off
	v_lshl_add_u64 v[150:151], v[158:159], 0, s[24:25]
	s_add_i32 m0, s37, 0x2000
	s_nop 0
	global_load_lds_dwordx4 v[150:151], off
	s_barrier
	s_waitcnt lgkmcnt(0)
	s_waitcnt lgkmcnt(0)
	v_mfma_f32_16x16x32_bf16 v[108:111], v[202:205], v[166:169], v[108:111]
	v_mfma_f32_16x16x32_bf16 v[100:103], v[210:213], v[166:169], v[100:103]
	v_mfma_f32_16x16x32_bf16 v[92:95], v[202:205], v[174:177], v[92:95]
	v_mfma_f32_16x16x32_bf16 v[84:87], v[210:213], v[174:177], v[84:87]
	v_mfma_f32_16x16x32_bf16 v[76:79], v[202:205], v[186:189], v[76:79]
	v_mfma_f32_16x16x32_bf16 v[72:75], v[210:213], v[186:189], v[72:75]
	v_mfma_f32_16x16x32_bf16 v[68:71], v[202:205], v[194:197], v[68:71]
	v_mfma_f32_16x16x32_bf16 v[64:67], v[210:213], v[194:197], v[64:67]
	v_mfma_f32_16x16x32_bf16 v[108:111], v[206:209], v[170:173], v[108:111]
	v_mfma_f32_16x16x32_bf16 v[100:103], v[214:217], v[170:173], v[100:103]
	v_mfma_f32_16x16x32_bf16 v[92:95], v[206:209], v[178:181], v[92:95]
	v_mfma_f32_16x16x32_bf16 v[84:87], v[214:217], v[178:181], v[84:87]
	v_mfma_f32_16x16x32_bf16 v[76:79], v[206:209], v[190:193], v[76:79]
	v_mfma_f32_16x16x32_bf16 v[72:75], v[214:217], v[190:193], v[72:75]
	v_mfma_f32_16x16x32_bf16 v[68:71], v[206:209], v[198:201], v[68:71]
	v_mfma_f32_16x16x32_bf16 v[64:67], v[214:217], v[198:201], v[64:67]
	s_mov_b32 m0, s50
	v_lshl_add_u64 v[150:151], v[182:183], 0, s[24:25]
	s_barrier
	ds_read_b128 v[166:169], v156 offset:49152
	ds_read_b128 v[170:173], v156 offset:50176
	ds_read_b128 v[174:177], v156 offset:51200
	ds_read_b128 v[178:181], v156 offset:52224
	ds_read_b128 v[186:189], v156 offset:53248
	ds_read_b128 v[190:193], v156 offset:54272
	ds_read_b128 v[194:197], v156 offset:55296
	ds_read_b128 v[198:201], v156 offset:56320
	global_load_lds_dwordx4 v[150:151], off
	v_lshl_add_u64 v[150:151], v[218:219], 0, s[24:25]
	s_mov_b32 m0, s51
	s_nop 0
	global_load_lds_dwordx4 v[150:151], off
	s_barrier
; #define PG8_STAGE(bufoff, gbase, voff) do { _Pragma("unroll") for (int _i = 0; _i < 2; ++_i) \
;         __builtin_amdgcn_global_load_lds((const unsigned*)((const char*)(gbase) + (voff)[_i]), (LAS unsigned*)(lds + (bufoff) + ldsw + _i * 8192), 16, 0, 0); } while (0)
; #define PG8_MMA(ai, bj, At, Bt) do { __builtin_amdgcn_s_setprio(1); _Pragma("unroll") for (int m = 0; m < 4; ++m) _Pragma("unroll") for (int n = 0; n < 2; ++n) _Pragma("unroll") for (int k = 0; k < 2; ++k) \
;         acc[ai][bj][m][n] = __builtin_amdgcn_mfma_f32_16x16x32_bf16(Bt[n][k], At[m][k], acc[ai][bj][m][n], 0, 0, 0); __builtin_amdgcn_s_setprio(0); } while (0)
; #define PG8_WAIT_V(n) asm volatile("s_waitcnt vmcnt(" #n ")" ::: "memory")
; #define PG8_WAIT_L(n) asm volatile("s_waitcnt lgkmcnt(" #n ")" ::: "memory")
; #define PG8_BAR __builtin_amdgcn_s_barrier()
; #define PG8_SCHED __builtin_amdgcn_sched_barrier(0)
; template <class Epi, class Sched>
; __device__ __forceinline__ void gemm_phase(LAS unsigned char* lds, const Gemm g, const Sched& S, const Epi& E) {
;     ...
;             PG8_BAR; PG8_WAIT_L(0); if constexpr (!Epi::DIAG) PG8_MMA(1, 0, At, B0); PG8_BAR; PG8_SCHED;
;             PG8_STAGE(PG8_SB(1, 1), b3 + hstepB, voffB);
;             PG8_WAIT_V(6); PG8_BAR; PG8_MMA(1, 1, At, B1); PG8_BAR;
;         }
;         E(acc, cur, wr, wc, fr, fq);
;     __device__ __forceinline__ void operator()(const Acc& acc, const Unit& u, int wr, int wc, int fr, int fq) const {
;     ...
; #pragma unroll
;         for (int ai = 0; ai < 2; ++ai)
; #pragma unroll
;             for (int m = 0; m < 4; ++m) { const int row = row0 + ai * HALF + m * 16; const int b = bidx_of_row(row);
;                 const float* xr = (row < TP) ? x0p + (size_t)row * DM : x0s + (size_t)(row - TP) * DM; const float* gr = gate + (size_t)b * MODW; float* orow = X1 + (size_t)row * DM;
; #pragma unroll
;                 for (int bj = 0; bj < 2; ++bj)
; #pragma unroll
;                     for (int n = 0; n < 2; ++n) { const int c = col0 + bj * HALF + n * 16; const f32x4 xv = *(const f32x4*)(xr + c), gv = *(const f32x4*)(gr + c);
;                         *(f32x4*)(orow + c) = xv + gv * acc[ai][bj][m][n]; } }
	s_waitcnt lgkmcnt(0)
	s_waitcnt lgkmcnt(0)
	v_mfma_f32_16x16x32_bf16 v[60:63], v[138:141], v[166:169], v[60:63]
	v_mfma_f32_16x16x32_bf16 v[56:59], v[146:149], v[166:169], v[56:59]
	v_mfma_f32_16x16x32_bf16 v[52:55], v[138:141], v[174:177], v[52:55]
	v_mfma_f32_16x16x32_bf16 v[48:51], v[146:149], v[174:177], v[48:51]
	v_mfma_f32_16x16x32_bf16 v[40:43], v[138:141], v[186:189], v[40:43]
	v_mfma_f32_16x16x32_bf16 v[32:35], v[146:149], v[186:189], v[32:35]
	v_mfma_f32_16x16x32_bf16 v[24:27], v[138:141], v[194:197], v[24:27]
	v_mfma_f32_16x16x32_bf16 v[16:19], v[146:149], v[194:197], v[16:19]
	v_mfma_f32_16x16x32_bf16 v[60:63], v[142:145], v[170:173], v[60:63]
	v_mfma_f32_16x16x32_bf16 v[56:59], v[162:165], v[170:173], v[56:59]
	v_mfma_f32_16x16x32_bf16 v[52:55], v[142:145], v[178:181], v[52:55]
	v_mfma_f32_16x16x32_bf16 v[48:51], v[162:165], v[178:181], v[48:51]
	v_mfma_f32_16x16x32_bf16 v[40:43], v[142:145], v[190:193], v[40:43]
	v_mfma_f32_16x16x32_bf16 v[32:35], v[162:165], v[190:193], v[32:35]
	v_mfma_f32_16x16x32_bf16 v[24:27], v[142:145], v[198:201], v[24:27]
	v_mfma_f32_16x16x32_bf16 v[16:19], v[162:165], v[198:201], v[16:19]
	s_barrier
	s_add_u32 s34, s34, 0x80080
	s_addc_u32 s35, s35, 0
	s_add_i32 s36, s36, s42
	v_lshl_add_u64 v[138:139], s[34:35], 0, v[128:129]
	s_mov_b32 m0, s36
	s_nop 0
	global_load_lds_dwordx4 v[138:139], off
	v_lshl_add_u64 v[138:139], s[34:35], 0, v[130:131]
	s_add_i32 m0, s36, 0x2000
	s_nop 0
	global_load_lds_dwordx4 v[138:139], off
	s_waitcnt vmcnt(6)
	s_barrier
	v_mfma_f32_16x16x32_bf16 v[44:47], v[202:205], v[166:169], v[44:47]
	v_mfma_f32_16x16x32_bf16 v[36:39], v[210:213], v[166:169], v[36:39]
	v_mfma_f32_16x16x32_bf16 v[28:31], v[202:205], v[174:177], v[28:31]
	v_mfma_f32_16x16x32_bf16 v[20:23], v[210:213], v[174:177], v[20:23]
	v_mfma_f32_16x16x32_bf16 v[12:15], v[202:205], v[186:189], v[12:15]
	v_mfma_f32_16x16x32_bf16 v[8:11], v[210:213], v[186:189], v[8:11]
	v_mfma_f32_16x16x32_bf16 v[4:7], v[202:205], v[194:197], v[4:7]
	v_mfma_f32_16x16x32_bf16 v[0:3], v[210:213], v[194:197], v[0:3]
	v_mfma_f32_16x16x32_bf16 v[44:47], v[206:209], v[170:173], v[44:47]
	v_mfma_f32_16x16x32_bf16 v[36:39], v[214:217], v[170:173], v[36:39]
	v_mfma_f32_16x16x32_bf16 v[28:31], v[206:209], v[178:181], v[28:31]
	v_mfma_f32_16x16x32_bf16 v[20:23], v[214:217], v[178:181], v[20:23]
	v_mfma_f32_16x16x32_bf16 v[12:15], v[206:209], v[190:193], v[12:15]
	v_mfma_f32_16x16x32_bf16 v[8:11], v[214:217], v[190:193], v[8:11]
	v_mfma_f32_16x16x32_bf16 v[4:7], v[206:209], v[198:201], v[4:7]
	v_mfma_f32_16x16x32_bf16 v[0:3], v[214:217], v[198:201], v[0:3]
	s_add_u32 s80, s80, 0x100
	s_and_b32 s80, s80, 0xfff
	s_cmp_ge_u32 s75, s67
	s_mov_b32 s34, s75
	s_barrier
	s_cbranch_scc0 .LBB0_1653
	s_setprio 0
	s_lshl_b32 s13, s69, 8
	s_add_i32 s13, s13, s52
	v_or_b32_e32 v138, s13, v152
	v_lshl_or_b32 v142, s68, 8, v154
	s_cmp_gt_i32 s16, -1
	v_add_u32_e32 v140, 0xffffe000, v138
	s_mov_b64 s[6:7], -1
	s_cbranch_scc1 .LBB0_1688
	v_cmp_gt_i32_e32 vcc, s47, v138
	v_cmp_lt_i32_e64 s[6:7], s56, v138
	s_and_saveexec_b64 s[34:35], s[6:7]
	s_xor_b64 s[6:7], exec, s[34:35]
	v_mov_b32_e32 v141, v133
	v_lshlrev_b64 v[144:145], 13, v[140:141]
	v_mov_b32_e32 v139, v133
	v_lshl_add_u64 v[148:149], s[10:11], 0, v[144:145]
	v_lshlrev_b64 v[146:147], 13, v[138:139]
	s_andn2_saveexec_b64 s[6:7], s[6:7]
	v_ashrrev_i32_e32 v139, 31, v138
	v_lshlrev_b64 v[146:147], 13, v[138:139]
	v_lshl_add_u64 v[148:149], s[8:9], 0, v[146:147]
	s_or_b64 exec, exec, s[6:7]
	s_ashr_i32 s13, s13, 11
	v_lshrrev_b32_e32 v132, 2, v140
	v_or_b32_e32 v132, 4, v132
	v_mov_b32_e32 v139, s13
	v_cndmask_b32_e32 v132, v132, v139, vcc
	v_mov_b64_e32 v[144:145], s[22:23]
	v_ashrrev_i32_e32 v143, 31, v142
	v_mad_i64_i32 v[158:159], s[6:7], v132, s54, v[144:145]
	v_lshlrev_b64 v[144:145], 2, v[142:143]
	v_lshl_add_u64 v[166:167], v[148:149], 0, v[144:145]
	v_lshl_add_u64 v[158:159], v[158:159], 0, v[144:145]
	global_load_dwordx4 v[186:189], v[166:167], off
	global_load_dwordx4 v[202:205], v[158:159], off
	global_load_dwordx4 v[190:193], v[166:167], off offset:64
	global_load_dwordx4 v[206:209], v[158:159], off offset:64
	global_load_dwordx4 v[194:197], v[166:167], off offset:512
	global_load_dwordx4 v[210:213], v[158:159], off offset:512
	global_load_dwordx4 v[198:201], v[166:167], off offset:576
	global_load_dwordx4 v[214:217], v[158:159], off offset:576
	v_lshl_add_u64 v[146:147], s[26:27], 0, v[146:147]
	v_lshl_add_u64 v[168:169], v[146:147], 0, v[144:145]
	v_add_u32_e32 v132, 0xffffe010, v138
	s_waitcnt vmcnt(6)
	v_pk_fma_f32 v[188:189], v[126:127], v[204:205], v[188:189]
	v_pk_fma_f32 v[186:187], v[124:125], v[202:203], v[186:187]
	global_store_dwordx4 v[168:169], v[186:189], off
	v_or_b32_e32 v150, 16, v138
	v_cmp_gt_i32_e32 vcc, s47, v150
	v_cmp_lt_i32_e64 s[6:7], s56, v150
	s_waitcnt vmcnt(5)
	v_pk_fma_f32 v[192:193], v[122:123], v[208:209], v[192:193]
	v_pk_fma_f32 v[190:191], v[120:121], v[206:207], v[190:191]
	global_store_dwordx4 v[168:169], v[190:193], off offset:64
	s_waitcnt vmcnt(4)
	v_pk_fma_f32 v[196:197], v[110:111], v[212:213], v[196:197]
	v_pk_fma_f32 v[194:195], v[108:109], v[210:211], v[194:195]
	global_store_dwordx4 v[168:169], v[194:197], off offset:512
	s_waitcnt vmcnt(3)
;     __device__ __forceinline__ void operator()(const Acc& acc, const Unit& u, int wr, int wc, int fr, int fq) const {
;     ...
;         for (int ai = 0; ai < 2; ++ai)
; #pragma unroll
;             for (int m = 0; m < 4; ++m) { const int row = row0 + ai * HALF + m * 16; const int b = bidx_of_row(row);
;                 const float* xr = (row < TP) ? x0p + (size_t)row * DM : x0s + (size_t)(row - TP) * DM; const float* gr = gate + (size_t)b * MODW; float* orow = X1 + (size_t)row * DM;
; #pragma unroll
;                 for (int bj = 0; bj < 2; ++bj)
; #pragma unroll
;                     for (int n = 0; n < 2; ++n) { const int c = col0 + bj * HALF + n * 16; const f32x4 xv = *(const f32x4*)(xr + c), gv = *(const f32x4*)(gr + c);
;                         *(f32x4*)(orow + c) = xv + gv * acc[ai][bj][m][n]; } }
	v_pk_fma_f32 v[200:201], v[102:103], v[216:217], v[200:201]
	v_pk_fma_f32 v[198:199], v[100:101], v[214:215], v[198:199]
	global_store_dwordx4 v[168:169], v[198:201], off offset:576
	s_and_saveexec_b64 s[34:35], s[6:7]
	s_xor_b64 s[6:7], exec, s[34:35]
	v_lshlrev_b64 v[146:147], 13, v[132:133]
	v_mov_b32_e32 v151, v133
	v_lshl_add_u64 v[148:149], s[10:11], 0, v[146:147]
	v_lshlrev_b64 v[146:147], 13, v[150:151]
	s_andn2_saveexec_b64 s[6:7], s[6:7]
	v_ashrrev_i32_e32 v151, 31, v150
	v_lshlrev_b64 v[146:147], 13, v[150:151]
	v_lshl_add_u64 v[148:149], s[8:9], 0, v[146:147]
	s_or_b64 exec, exec, s[6:7]
	v_lshrrev_b32_e32 v132, 2, v132
	v_add_u32_e32 v132, 4, v132
	v_mov_b32_e32 v139, s13
	v_cndmask_b32_e32 v132, v132, v139, vcc
	v_mov_b64_e32 v[150:151], s[22:23]
	v_mad_i64_i32 v[158:159], s[6:7], v132, s54, v[150:151]
	v_lshl_add_u64 v[166:167], v[148:149], 0, v[144:145]
	v_lshl_add_u64 v[158:159], v[158:159], 0, v[144:145]
	global_load_dwordx4 v[186:189], v[166:167], off
	global_load_dwordx4 v[202:205], v[158:159], off
	global_load_dwordx4 v[190:193], v[166:167], off offset:64
	global_load_dwordx4 v[206:209], v[158:159], off offset:64
	global_load_dwordx4 v[194:197], v[166:167], off offset:512
	global_load_dwordx4 v[210:213], v[158:159], off offset:512
	global_load_dwordx4 v[198:201], v[166:167], off offset:576
	global_load_dwordx4 v[214:217], v[158:159], off offset:576
	v_lshl_add_u64 v[146:147], s[26:27], 0, v[146:147]
	v_lshl_add_u64 v[168:169], v[146:147], 0, v[144:145]
	v_add_u32_e32 v132, 0xffffe020, v138
	s_waitcnt vmcnt(6)
	v_pk_fma_f32 v[188:189], v[118:119], v[204:205], v[188:189]
	v_pk_fma_f32 v[186:187], v[116:117], v[202:203], v[186:187]
	global_store_dwordx4 v[168:169], v[186:189], off
	v_or_b32_e32 v150, 32, v138
	v_cmp_gt_i32_e32 vcc, s47, v150
	v_cmp_lt_i32_e64 s[6:7], s56, v150
	s_waitcnt vmcnt(5)
	v_pk_fma_f32 v[192:193], v[114:115], v[208:209], v[192:193]
	v_pk_fma_f32 v[190:191], v[112:113], v[206:207], v[190:191]
	global_store_dwordx4 v[168:169], v[190:193], off offset:64
	s_waitcnt vmcnt(4)
	v_pk_fma_f32 v[196:197], v[94:95], v[212:213], v[196:197]
	v_pk_fma_f32 v[194:195], v[92:93], v[210:211], v[194:195]
	global_store_dwordx4 v[168:169], v[194:197], off offset:512
	s_waitcnt vmcnt(3)
	v_pk_fma_f32 v[200:201], v[86:87], v[216:217], v[200:201]
	v_pk_fma_f32 v[198:199], v[84:85], v[214:215], v[198:199]
	global_store_dwordx4 v[168:169], v[198:201], off offset:576
	s_and_saveexec_b64 s[34:35], s[6:7]
	s_xor_b64 s[6:7], exec, s[34:35]
	v_lshlrev_b64 v[146:147], 13, v[132:133]
	v_mov_b32_e32 v151, v133
	v_lshl_add_u64 v[148:149], s[10:11], 0, v[146:147]
	v_lshlrev_b64 v[146:147], 13, v[150:151]
	s_andn2_saveexec_b64 s[6:7], s[6:7]
	v_ashrrev_i32_e32 v151, 31, v150
	v_lshlrev_b64 v[146:147], 13, v[150:151]
	v_lshl_add_u64 v[148:149], s[8:9], 0, v[146:147]
	s_or_b64 exec, exec, s[6:7]
	v_lshrrev_b32_e32 v132, 2, v132
	v_or_b32_e32 v132, 4, v132
	v_mov_b32_e32 v139, s13
	v_cndmask_b32_e32 v132, v132, v139, vcc
	v_mov_b64_e32 v[150:151], s[22:23]
	v_mad_i64_i32 v[158:159], s[6:7], v132, s54, v[150:151]
	v_lshl_add_u64 v[166:167], v[148:149], 0, v[144:145]
	v_lshl_add_u64 v[158:159], v[158:159], 0, v[144:145]
	global_load_dwordx4 v[186:189], v[166:167], off
	global_load_dwordx4 v[202:205], v[158:159], off
	global_load_dwordx4 v[190:193], v[166:167], off offset:64
	global_load_dwordx4 v[206:209], v[158:159], off offset:64
	global_load_dwordx4 v[194:197], v[166:167], off offset:512
	global_load_dwordx4 v[210:213], v[158:159], off offset:512
	global_load_dwordx4 v[198:201], v[166:167], off offset:576
	global_load_dwordx4 v[214:217], v[158:159], off offset:576
	v_lshl_add_u64 v[146:147], s[26:27], 0, v[146:147]
	v_lshl_add_u64 v[168:169], v[146:147], 0, v[144:145]
	v_add_u32_e32 v132, 0xffffe030, v138
	s_waitcnt vmcnt(6)
	v_pk_fma_f32 v[188:189], v[106:107], v[204:205], v[188:189]
	v_pk_fma_f32 v[186:187], v[104:105], v[202:203], v[186:187]
	global_store_dwordx4 v[168:169], v[186:189], off
	v_or_b32_e32 v150, 48, v138
	v_cmp_gt_i32_e32 vcc, s47, v150
	v_cmp_lt_i32_e64 s[6:7], s56, v150
	s_waitcnt vmcnt(5)
	v_pk_fma_f32 v[192:193], v[98:99], v[208:209], v[192:193]
	v_pk_fma_f32 v[190:191], v[96:97], v[206:207], v[190:191]
	global_store_dwordx4 v[168:169], v[190:193], off offset:64
	s_waitcnt vmcnt(4)
	v_pk_fma_f32 v[196:197], v[78:79], v[212:213], v[196:197]
	v_pk_fma_f32 v[194:195], v[76:77], v[210:211], v[194:195]
	global_store_dwordx4 v[168:169], v[194:197], off offset:512
	s_waitcnt vmcnt(3)
	v_pk_fma_f32 v[200:201], v[74:75], v[216:217], v[200:201]
	v_pk_fma_f32 v[198:199], v[72:73], v[214:215], v[198:199]
	global_store_dwordx4 v[168:169], v[198:201], off offset:576
	s_and_saveexec_b64 s[34:35], s[6:7]
	s_xor_b64 s[6:7], exec, s[34:35]
	v_lshlrev_b64 v[146:147], 13, v[132:133]
	v_mov_b32_e32 v151, v133
	v_lshl_add_u64 v[148:149], s[10:11], 0, v[146:147]
	v_lshlrev_b64 v[146:147], 13, v[150:151]
	s_andn2_saveexec_b64 s[6:7], s[6:7]
	v_ashrrev_i32_e32 v151, 31, v150
	v_lshlrev_b64 v[146:147], 13, v[150:151]
	v_lshl_add_u64 v[148:149], s[8:9], 0, v[146:147]
	s_or_b64 exec, exec, s[6:7]
	v_lshrrev_b32_e32 v132, 2, v132
	v_add_u32_e32 v132, 4, v132
	v_mov_b32_e32 v139, s13
	v_cndmask_b32_e32 v132, v132, v139, vcc
	v_mov_b64_e32 v[150:151], s[22:23]
	v_mad_i64_i32 v[158:159], s[6:7], v132, s54, v[150:151]
	v_lshl_add_u64 v[166:167], v[148:149], 0, v[144:145]
	v_lshl_add_u64 v[158:159], v[158:159], 0, v[144:145]
	global_load_dwordx4 v[186:189], v[166:167], off
	global_load_dwordx4 v[202:205], v[158:159], off
	global_load_dwordx4 v[190:193], v[166:167], off offset:64
	global_load_dwordx4 v[206:209], v[158:159], off offset:64
	global_load_dwordx4 v[194:197], v[166:167], off offset:512
	global_load_dwordx4 v[210:213], v[158:159], off offset:512
	global_load_dwordx4 v[198:201], v[166:167], off offset:576
	global_load_dwordx4 v[214:217], v[158:159], off offset:576
	v_lshl_add_u64 v[146:147], s[26:27], 0, v[146:147]
	v_lshl_add_u64 v[168:169], v[146:147], 0, v[144:145]
	v_cmp_gt_i32_e32 vcc, s57, v138
	v_cmp_lt_i32_e64 s[6:7], s58, v138
	v_add_u32_e32 v132, 0xffffe080, v138
	s_waitcnt vmcnt(6)
;     __device__ __forceinline__ void operator()(const Acc& acc, const Unit& u, int wr, int wc, int fr, int fq) const {
;     ...
;         for (int ai = 0; ai < 2; ++ai)
; #pragma unroll
;             for (int m = 0; m < 4; ++m) { const int row = row0 + ai * HALF + m * 16; const int b = bidx_of_row(row);
;                 const float* xr = (row < TP) ? x0p + (size_t)row * DM : x0s + (size_t)(row - TP) * DM; const float* gr = gate + (size_t)b * MODW; float* orow = X1 + (size_t)row * DM;
; #pragma unroll
;                 for (int bj = 0; bj < 2; ++bj)
; #pragma unroll
;                     for (int n = 0; n < 2; ++n) { const int c = col0 + bj * HALF + n * 16; const f32x4 xv = *(const f32x4*)(xr + c), gv = *(const f32x4*)(gr + c);
;                         *(f32x4*)(orow + c) = xv + gv * acc[ai][bj][m][n]; } }
	v_pk_fma_f32 v[188:189], v[90:91], v[204:205], v[188:189]
	v_pk_fma_f32 v[186:187], v[88:89], v[202:203], v[186:187]
	global_store_dwordx4 v[168:169], v[186:189], off
	s_waitcnt vmcnt(5)
	v_pk_fma_f32 v[192:193], v[82:83], v[208:209], v[192:193]
	v_pk_fma_f32 v[190:191], v[80:81], v[206:207], v[190:191]
	global_store_dwordx4 v[168:169], v[190:193], off offset:64
	s_waitcnt vmcnt(4)
	v_pk_fma_f32 v[196:197], v[70:71], v[212:213], v[196:197]
	v_pk_fma_f32 v[194:195], v[68:69], v[210:211], v[194:195]
	global_store_dwordx4 v[168:169], v[194:197], off offset:512
	v_add_u32_e32 v146, 0x80, v138
	s_waitcnt vmcnt(3)
	v_pk_fma_f32 v[200:201], v[66:67], v[216:217], v[200:201]
	v_pk_fma_f32 v[198:199], v[64:65], v[214:215], v[198:199]
	global_store_dwordx4 v[168:169], v[198:201], off offset:576
	s_and_saveexec_b64 s[34:35], s[6:7]
	s_xor_b64 s[6:7], exec, s[34:35]
	v_lshlrev_b64 v[148:149], 13, v[132:133]
	v_mov_b32_e32 v147, v133
	v_lshl_add_u64 v[150:151], s[10:11], 0, v[148:149]
	v_lshlrev_b64 v[148:149], 13, v[146:147]
	s_andn2_saveexec_b64 s[6:7], s[6:7]
	v_ashrrev_i32_e32 v147, 31, v146
	v_lshlrev_b64 v[148:149], 13, v[146:147]
	v_lshl_add_u64 v[150:151], s[8:9], 0, v[148:149]
	s_or_b64 exec, exec, s[6:7]
	v_lshrrev_b32_e32 v132, 2, v132
	v_ashrrev_i32_e32 v139, 11, v146
	v_or_b32_e32 v132, 4, v132
	v_cndmask_b32_e32 v132, v132, v139, vcc
	v_mov_b64_e32 v[146:147], s[22:23]
	v_mad_i64_i32 v[146:147], s[6:7], v132, s54, v[146:147]
	v_lshl_add_u64 v[150:151], v[150:151], 0, v[144:145]
	v_lshl_add_u64 v[158:159], v[146:147], 0, v[144:145]
	global_load_dwordx4 v[186:189], v[150:151], off
	global_load_dwordx4 v[202:205], v[158:159], off
	global_load_dwordx4 v[190:193], v[150:151], off offset:64
	global_load_dwordx4 v[206:209], v[158:159], off offset:64
	global_load_dwordx4 v[194:197], v[150:151], off offset:512
	global_load_dwordx4 v[210:213], v[158:159], off offset:512
	global_load_dwordx4 v[198:201], v[150:151], off offset:576
	global_load_dwordx4 v[214:217], v[158:159], off offset:576
	v_lshl_add_u64 v[146:147], s[26:27], 0, v[148:149]
	v_lshl_add_u64 v[170:171], v[146:147], 0, v[144:145]
	v_cmp_gt_i32_e32 vcc, s59, v138
	v_cmp_lt_i32_e64 s[6:7], s60, v138
	v_add_u32_e32 v132, 0xffffe090, v138
	s_waitcnt vmcnt(6)
	v_pk_fma_f32 v[148:149], v[62:63], v[204:205], v[188:189]
	v_pk_fma_f32 v[146:147], v[60:61], v[202:203], v[186:187]
	global_store_dwordx4 v[170:171], v[146:149], off
	s_waitcnt vmcnt(5)
	v_pk_fma_f32 v[192:193], v[58:59], v[208:209], v[192:193]
	v_pk_fma_f32 v[190:191], v[56:57], v[206:207], v[190:191]
	global_store_dwordx4 v[170:171], v[190:193], off offset:64
	s_waitcnt vmcnt(4)
	v_pk_fma_f32 v[196:197], v[46:47], v[212:213], v[196:197]
	v_pk_fma_f32 v[194:195], v[44:45], v[210:211], v[194:195]
	global_store_dwordx4 v[170:171], v[194:197], off offset:512
	v_add_u32_e32 v150, 0x90, v138
	s_waitcnt vmcnt(3)
	v_pk_fma_f32 v[200:201], v[38:39], v[216:217], v[200:201]
	v_pk_fma_f32 v[198:199], v[36:37], v[214:215], v[198:199]
	global_store_dwordx4 v[170:171], v[198:201], off offset:576
	s_and_saveexec_b64 s[34:35], s[6:7]
	s_xor_b64 s[6:7], exec, s[34:35]
	v_lshlrev_b64 v[146:147], 13, v[132:133]
	v_mov_b32_e32 v151, v133
	v_lshl_add_u64 v[148:149], s[10:11], 0, v[146:147]
	v_lshlrev_b64 v[146:147], 13, v[150:151]
	s_andn2_saveexec_b64 s[6:7], s[6:7]
	v_ashrrev_i32_e32 v151, 31, v150
	v_lshlrev_b64 v[146:147], 13, v[150:151]
	v_lshl_add_u64 v[148:149], s[8:9], 0, v[146:147]
	s_or_b64 exec, exec, s[6:7]
	v_lshrrev_b32_e32 v132, 2, v132
	v_add_u32_e32 v132, 4, v132
	v_cndmask_b32_e32 v132, v132, v139, vcc
	v_mov_b64_e32 v[150:151], s[22:23]
	v_mad_i64_i32 v[158:159], s[6:7], v132, s54, v[150:151]
	v_lshl_add_u64 v[166:167], v[148:149], 0, v[144:145]
	v_lshl_add_u64 v[158:159], v[158:159], 0, v[144:145]
	global_load_dwordx4 v[186:189], v[166:167], off
	global_load_dwordx4 v[202:205], v[158:159], off
	global_load_dwordx4 v[190:193], v[166:167], off offset:64
	global_load_dwordx4 v[206:209], v[158:159], off offset:64
	global_load_dwordx4 v[194:197], v[166:167], off offset:512
	global_load_dwordx4 v[210:213], v[158:159], off offset:512
	global_load_dwordx4 v[198:201], v[166:167], off offset:576
	global_load_dwordx4 v[214:217], v[158:159], off offset:576
	v_lshl_add_u64 v[146:147], s[26:27], 0, v[146:147]
	v_lshl_add_u64 v[168:169], v[146:147], 0, v[144:145]
	v_cmp_gt_i32_e32 vcc, s61, v138
	v_cmp_lt_i32_e64 s[6:7], s62, v138
	v_add_u32_e32 v132, 0xffffe0a0, v138
	s_waitcnt vmcnt(6)
	v_pk_fma_f32 v[188:189], v[54:55], v[204:205], v[188:189]
	v_pk_fma_f32 v[186:187], v[52:53], v[202:203], v[186:187]
	global_store_dwordx4 v[168:169], v[186:189], off
	v_add_u32_e32 v150, 0xa0, v138
	s_waitcnt vmcnt(5)
;     __device__ __forceinline__ void operator()(const Acc& acc, const Unit& u, int wr, int wc, int fr, int fq) const {
;     ...
;         for (int ai = 0; ai < 2; ++ai)
; #pragma unroll
;             for (int m = 0; m < 4; ++m) { const int row = row0 + ai * HALF + m * 16; const int b = bidx_of_row(row);
;                 const float* xr = (row < TP) ? x0p + (size_t)row * DM : x0s + (size_t)(row - TP) * DM; const float* gr = gate + (size_t)b * MODW; float* orow = X1 + (size_t)row * DM;
; #pragma unroll
;                 for (int bj = 0; bj < 2; ++bj)
; #pragma unroll
;                     for (int n = 0; n < 2; ++n) { const int c = col0 + bj * HALF + n * 16; const f32x4 xv = *(const f32x4*)(xr + c), gv = *(const f32x4*)(gr + c);
;                         *(f32x4*)(orow + c) = xv + gv * acc[ai][bj][m][n]; } }
	v_pk_fma_f32 v[192:193], v[50:51], v[208:209], v[192:193]
	v_pk_fma_f32 v[190:191], v[48:49], v[206:207], v[190:191]
	global_store_dwordx4 v[168:169], v[190:193], off offset:64
	s_waitcnt vmcnt(4)
	v_pk_fma_f32 v[196:197], v[30:31], v[212:213], v[196:197]
	v_pk_fma_f32 v[194:195], v[28:29], v[210:211], v[194:195]
	global_store_dwordx4 v[168:169], v[194:197], off offset:512
	s_waitcnt vmcnt(3)
	v_pk_fma_f32 v[200:201], v[22:23], v[216:217], v[200:201]
	v_pk_fma_f32 v[198:199], v[20:21], v[214:215], v[198:199]
	global_store_dwordx4 v[168:169], v[198:201], off offset:576
	s_and_saveexec_b64 s[34:35], s[6:7]
	s_xor_b64 s[6:7], exec, s[34:35]
	v_lshlrev_b64 v[146:147], 13, v[132:133]
	v_mov_b32_e32 v151, v133
	v_lshl_add_u64 v[148:149], s[10:11], 0, v[146:147]
	v_lshlrev_b64 v[146:147], 13, v[150:151]
	s_andn2_saveexec_b64 s[6:7], s[6:7]
	v_ashrrev_i32_e32 v151, 31, v150
	v_lshlrev_b64 v[146:147], 13, v[150:151]
	v_lshl_add_u64 v[148:149], s[8:9], 0, v[146:147]
	s_or_b64 exec, exec, s[6:7]
	v_lshrrev_b32_e32 v132, 2, v132
	v_or_b32_e32 v132, 4, v132
	v_cndmask_b32_e32 v132, v132, v139, vcc
	v_mov_b64_e32 v[150:151], s[22:23]
	v_mad_i64_i32 v[158:159], s[6:7], v132, s54, v[150:151]
	v_lshl_add_u64 v[166:167], v[148:149], 0, v[144:145]
	v_lshl_add_u64 v[158:159], v[158:159], 0, v[144:145]
	global_load_dwordx4 v[186:189], v[166:167], off
	global_load_dwordx4 v[202:205], v[158:159], off
	global_load_dwordx4 v[190:193], v[166:167], off offset:64
	global_load_dwordx4 v[206:209], v[158:159], off offset:64
	global_load_dwordx4 v[194:197], v[166:167], off offset:512
	global_load_dwordx4 v[210:213], v[158:159], off offset:512
	global_load_dwordx4 v[198:201], v[166:167], off offset:576
	global_load_dwordx4 v[214:217], v[158:159], off offset:576
	v_lshl_add_u64 v[146:147], s[26:27], 0, v[146:147]
	v_lshl_add_u64 v[168:169], v[146:147], 0, v[144:145]
	v_cmp_gt_i32_e32 vcc, s63, v138
	v_cmp_lt_i32_e64 s[6:7], s64, v138
	v_add_u32_e32 v132, 0xffffe0b0, v138
	s_waitcnt vmcnt(6)
	v_pk_fma_f32 v[188:189], v[42:43], v[204:205], v[188:189]
	v_pk_fma_f32 v[186:187], v[40:41], v[202:203], v[186:187]
	global_store_dwordx4 v[168:169], v[186:189], off
	v_add_u32_e32 v150, 0xb0, v138
	s_waitcnt vmcnt(5)
	v_pk_fma_f32 v[192:193], v[34:35], v[208:209], v[192:193]
	v_pk_fma_f32 v[190:191], v[32:33], v[206:207], v[190:191]
	global_store_dwordx4 v[168:169], v[190:193], off offset:64
	s_waitcnt vmcnt(4)
	v_pk_fma_f32 v[196:197], v[14:15], v[212:213], v[196:197]
	v_pk_fma_f32 v[194:195], v[12:13], v[210:211], v[194:195]
	global_store_dwordx4 v[168:169], v[194:197], off offset:512
	s_waitcnt vmcnt(3)
	v_pk_fma_f32 v[200:201], v[10:11], v[216:217], v[200:201]
	v_pk_fma_f32 v[198:199], v[8:9], v[214:215], v[198:199]
	global_store_dwordx4 v[168:169], v[198:201], off offset:576
	s_and_saveexec_b64 s[34:35], s[6:7]
	s_xor_b64 s[6:7], exec, s[34:35]
	v_lshlrev_b64 v[146:147], 13, v[132:133]
	v_mov_b32_e32 v151, v133
	v_lshl_add_u64 v[148:149], s[10:11], 0, v[146:147]
	v_lshlrev_b64 v[146:147], 13, v[150:151]
	s_andn2_saveexec_b64 s[6:7], s[6:7]
	v_ashrrev_i32_e32 v151, 31, v150
	v_lshlrev_b64 v[146:147], 13, v[150:151]
	v_lshl_add_u64 v[148:149], s[8:9], 0, v[146:147]
	s_or_b64 exec, exec, s[6:7]
	v_lshrrev_b32_e32 v132, 2, v132
	v_add_u32_e32 v132, 4, v132
	v_cndmask_b32_e32 v132, v132, v139, vcc
	v_mov_b64_e32 v[150:151], s[22:23]
	v_mad_i64_i32 v[158:159], s[6:7], v132, s54, v[150:151]
	v_lshl_add_u64 v[166:167], v[148:149], 0, v[144:145]
	v_lshl_add_u64 v[158:159], v[158:159], 0, v[144:145]
	global_load_dwordx4 v[186:189], v[166:167], off
	global_load_dwordx4 v[202:205], v[158:159], off
	global_load_dwordx4 v[190:193], v[166:167], off offset:64
	global_load_dwordx4 v[206:209], v[158:159], off offset:64
	global_load_dwordx4 v[194:197], v[166:167], off offset:512
	global_load_dwordx4 v[210:213], v[158:159], off offset:512
	global_load_dwordx4 v[198:201], v[166:167], off offset:576
	global_load_dwordx4 v[214:217], v[158:159], off offset:576
	v_lshl_add_u64 v[146:147], s[26:27], 0, v[146:147]
	v_lshl_add_u64 v[168:169], v[146:147], 0, v[144:145]
	s_mov_b64 s[6:7], 0
	s_waitcnt vmcnt(6)
	v_pk_fma_f32 v[146:147], v[26:27], v[204:205], v[188:189]
	v_pk_fma_f32 v[144:145], v[24:25], v[202:203], v[186:187]
	global_store_dwordx4 v[168:169], v[144:147], off
	s_waitcnt vmcnt(5)
	v_pk_fma_f32 v[192:193], v[18:19], v[208:209], v[192:193]
	v_pk_fma_f32 v[190:191], v[16:17], v[206:207], v[190:191]
	global_store_dwordx4 v[168:169], v[190:193], off offset:64
	s_waitcnt vmcnt(4)
	v_pk_fma_f32 v[196:197], v[6:7], v[212:213], v[196:197]
	v_pk_fma_f32 v[194:195], v[4:5], v[210:211], v[194:195]
	global_store_dwordx4 v[168:169], v[194:197], off offset:512
	s_waitcnt vmcnt(3)
	v_pk_fma_f32 v[200:201], v[2:3], v[216:217], v[200:201]
	v_pk_fma_f32 v[198:199], v[0:1], v[214:215], v[198:199]
	global_store_dwordx4 v[168:169], v[198:201], off offset:576

; #define PG8_STAGE(bufoff, gbase, voff) do { _Pragma("unroll") for (int _i = 0; _i < 2; ++_i) \
;         __builtin_amdgcn_global_load_lds((const unsigned*)((const char*)(gbase) + (voff)[_i]), (LAS unsigned*)(lds + (bufoff) + ldsw + _i * 8192), 16, 0, 0); } while (0)
; #define PG8_LDA(dst, b, h) do { _Pragma("unroll") for (int m = 0; m < 4; ++m) _Pragma("unroll") for (int k = 0; k < 2; ++k) dst[m][k] = *(const LAS bf16x8*)(lds + PG8_SA(b, h) + aoff + m * 2048 + k * 1024); } while (0)
; #define PG8_LDB(dst, b, h) do { _Pragma("unroll") for (int n = 0; n < 2; ++n) _Pragma("unroll") for (int k = 0; k < 2; ++k) dst[n][k] = *(const LAS bf16x8*)(lds + PG8_SB(b, h) + boff + n * 2048 + k * 1024); } while (0)
; #define PG8_MMA(ai, bj, At, Bt) do { __builtin_amdgcn_s_setprio(1); _Pragma("unroll") for (int m = 0; m < 4; ++m) _Pragma("unroll") for (int n = 0; n < 2; ++n) _Pragma("unroll") for (int k = 0; k < 2; ++k) \
;         acc[ai][bj][m][n] = __builtin_amdgcn_mfma_f32_16x16x32_bf16(Bt[n][k], At[m][k], acc[ai][bj][m][n], 0, 0, 0); __builtin_amdgcn_s_setprio(0); } while (0)
; #define PG8_WAIT_L(n) asm volatile("s_waitcnt lgkmcnt(" #n ")" ::: "memory")
; #define PG8_BAR __builtin_amdgcn_s_barrier()
; #define PG8_SCHED __builtin_amdgcn_sched_barrier(0)
; template <class Epi, class Sched>
; __device__ __forceinline__ void gemm_phase(LAS unsigned char* lds, const Gemm g, const Sched& S, const Epi& E) {
;     ...
;             PG8_LDB(B0, 0, 0); PG8_SCHED; PG8_LDA(At, 0, 0); PG8_STAGE(PG8_SA(1, 1), a1 + hstepA, voffA);
;             PG8_WAIT_L(8); PG8_BAR; PG8_WAIT_L(0); PG8_MMA(0, 0, At, B0); PG8_BAR; PG8_SCHED;
;             PG8_LDB(B1, 0, 1); PG8_STAGE(PG8_SB(0, 0), b2, voffB);
;             PG8_BAR; PG8_WAIT_L(0); if constexpr (!Epi::DIAG) PG8_MMA(0, 1, At, B1); PG8_BAR;
;     ...
;         for (int a = 0; a < 2; ++a)
; #pragma unroll
;             for (int b = 0; b < 2; ++b)
; #pragma unroll
;                 for (int m = 0; m < 4; ++m)
; #pragma unroll
;                     for (int n = 0; n < 2; ++n) acc[a][b][m][n] = (f32x4){0.f, 0.f, 0.f, 0.f};
;         cur = nxt; cA = nA; cB = nB; ++ui;
.LBB0_1914:
	s_add_i32 s28, s66, -2
	s_add_u32 s6, s6, 0x160080
	s_addc_u32 s7, s7, 0
	s_add_u32 s29, s24, 0x100
	v_mov_b32_e32 v0, 0
	s_addc_u32 s67, s25, 0
	s_mov_b32 s24, 0
	v_mov_b32_e32 v1, v0
	v_mov_b32_e32 v2, v0
	v_mov_b32_e32 v3, v0
	v_mov_b32_e32 v4, v0
	v_mov_b32_e32 v5, v0
	v_mov_b32_e32 v6, v0
	v_mov_b32_e32 v7, v0
	v_mov_b32_e32 v8, v0
	v_mov_b32_e32 v9, v0
	v_mov_b32_e32 v10, v0
	v_mov_b32_e32 v11, v0
	v_mov_b32_e32 v12, v0
	v_mov_b32_e32 v13, v0
	v_mov_b32_e32 v14, v0
	v_mov_b32_e32 v15, v0
	v_mov_b32_e32 v20, v0
	v_mov_b32_e32 v21, v0
	v_mov_b32_e32 v22, v0
	v_mov_b32_e32 v23, v0
	v_mov_b32_e32 v28, v0
	v_mov_b32_e32 v29, v0
	v_mov_b32_e32 v30, v0
	v_mov_b32_e32 v31, v0
	v_mov_b32_e32 v36, v0
	v_mov_b32_e32 v37, v0
	v_mov_b32_e32 v38, v0
	v_mov_b32_e32 v39, v0
	v_mov_b32_e32 v44, v0
	v_mov_b32_e32 v45, v0
	v_mov_b32_e32 v46, v0
	v_mov_b32_e32 v47, v0
	v_mov_b32_e32 v16, v0
	v_mov_b32_e32 v17, v0
	v_mov_b32_e32 v18, v0
	v_mov_b32_e32 v19, v0
	v_mov_b32_e32 v24, v0
	v_mov_b32_e32 v25, v0
	v_mov_b32_e32 v26, v0
	v_mov_b32_e32 v27, v0
	v_mov_b32_e32 v32, v0
	v_mov_b32_e32 v33, v0
	v_mov_b32_e32 v34, v0
	v_mov_b32_e32 v35, v0
	v_mov_b32_e32 v40, v0
	v_mov_b32_e32 v41, v0
	v_mov_b32_e32 v42, v0
	v_mov_b32_e32 v43, v0
	v_mov_b32_e32 v48, v0
	v_mov_b32_e32 v49, v0
	v_mov_b32_e32 v50, v0
	v_mov_b32_e32 v51, v0
	v_mov_b32_e32 v52, v0
	v_mov_b32_e32 v53, v0
	v_mov_b32_e32 v54, v0
	v_mov_b32_e32 v55, v0
	v_mov_b32_e32 v56, v0
	v_mov_b32_e32 v57, v0
	v_mov_b32_e32 v58, v0
	v_mov_b32_e32 v59, v0
	v_mov_b32_e32 v60, v0
	v_mov_b32_e32 v61, v0
	v_mov_b32_e32 v62, v0
	v_mov_b32_e32 v63, v0
	v_mov_b32_e32 v64, v0
	v_mov_b32_e32 v65, v0
	v_mov_b32_e32 v66, v0
	v_mov_b32_e32 v67, v0
	v_mov_b32_e32 v68, v0
	v_mov_b32_e32 v69, v0
	v_mov_b32_e32 v70, v0
	v_mov_b32_e32 v71, v0
	v_mov_b32_e32 v72, v0
	v_mov_b32_e32 v73, v0
	v_mov_b32_e32 v74, v0
	v_mov_b32_e32 v75, v0
	v_mov_b32_e32 v76, v0
	v_mov_b32_e32 v77, v0
	v_mov_b32_e32 v78, v0
	v_mov_b32_e32 v79, v0
	v_mov_b32_e32 v84, v0
	v_mov_b32_e32 v85, v0
	v_mov_b32_e32 v86, v0
	v_mov_b32_e32 v87, v0
	v_mov_b32_e32 v92, v0
	v_mov_b32_e32 v93, v0
	v_mov_b32_e32 v94, v0
	v_mov_b32_e32 v95, v0
	v_mov_b32_e32 v100, v0
	v_mov_b32_e32 v101, v0
	v_mov_b32_e32 v102, v0
	v_mov_b32_e32 v103, v0
	v_mov_b32_e32 v108, v0
	v_mov_b32_e32 v109, v0
	v_mov_b32_e32 v110, v0
	v_mov_b32_e32 v111, v0
	v_mov_b32_e32 v80, v0
	v_mov_b32_e32 v81, v0
	v_mov_b32_e32 v82, v0
	v_mov_b32_e32 v83, v0
	v_mov_b32_e32 v88, v0
	v_mov_b32_e32 v89, v0
	v_mov_b32_e32 v90, v0
	v_mov_b32_e32 v91, v0
	v_mov_b32_e32 v96, v0
	v_mov_b32_e32 v97, v0
	v_mov_b32_e32 v98, v0
	v_mov_b32_e32 v99, v0
	v_mov_b32_e32 v104, v0
	v_mov_b32_e32 v105, v0
	v_mov_b32_e32 v106, v0
	v_mov_b32_e32 v107, v0
	v_mov_b32_e32 v112, v0
	v_mov_b32_e32 v113, v0
	v_mov_b32_e32 v114, v0
	v_mov_b32_e32 v115, v0
	v_mov_b32_e32 v116, v0
	v_mov_b32_e32 v117, v0
	v_mov_b32_e32 v118, v0
	v_mov_b32_e32 v119, v0
	v_mov_b32_e32 v120, v0
	v_mov_b32_e32 v121, v0
	v_mov_b32_e32 v122, v0
	v_mov_b32_e32 v123, v0
	v_mov_b32_e32 v124, v0
	v_mov_b32_e32 v125, v0
	v_mov_b32_e32 v126, v0
	v_mov_b32_e32 v127, v0
	s_lshr_b32 s80, s3, 8
	s_cmp_lg_u32 s80, 0
	s_cbranch_scc0 .Lprio_1915
	s_setprio 1
.Lprio_1915:
.LBB0_1915:
	ds_read_b128 v[138:141], v155
	ds_read_b128 v[142:145], v155 offset:1024
	ds_read_b128 v[146:149], v155 offset:2048
	ds_read_b128 v[162:165], v155 offset:3072
	s_add_i32 s68, s24, 2
	s_add_u32 s25, s6, 0xffea0080
	s_addc_u32 s26, s7, -1
	s_cmp_eq_u32 s28, s24
	s_cselect_b32 s24, s22, s29
	s_cselect_b32 s27, s21, s26
	s_cselect_b32 s26, s20, s25
	s_cselect_b32 s25, s23, s67
	v_lshl_add_u64 v[150:151], s[6:7], 0, v[134:135]
	s_add_i32 m0, s37, 0xc000
	ds_read_b128 v[166:169], v156
	ds_read_b128 v[170:173], v156 offset:1024
	ds_read_b128 v[174:177], v156 offset:2048
	ds_read_b128 v[178:181], v156 offset:3072
	ds_read_b128 v[186:189], v156 offset:4096
	ds_read_b128 v[190:193], v156 offset:5120
	ds_read_b128 v[194:197], v156 offset:6144
	ds_read_b128 v[198:201], v156 offset:7168
	global_load_lds_dwordx4 v[150:151], off
	v_lshl_add_u64 v[150:151], s[6:7], 0, v[136:137]
	s_add_i32 m0, s37, 0xe000
	s_nop 0
	global_load_lds_dwordx4 v[150:151], off
	s_waitcnt lgkmcnt(8)
	s_barrier
	s_waitcnt lgkmcnt(0)
	s_waitcnt lgkmcnt(0)
	v_mfma_f32_16x16x32_bf16 v[124:127], v[138:141], v[166:169], v[124:127]
	v_mfma_f32_16x16x32_bf16 v[120:123], v[146:149], v[166:169], v[120:123]
	v_mfma_f32_16x16x32_bf16 v[116:119], v[138:141], v[174:177], v[116:119]
	v_mfma_f32_16x16x32_bf16 v[112:115], v[146:149], v[174:177], v[112:115]
	v_mfma_f32_16x16x32_bf16 v[104:107], v[138:141], v[186:189], v[104:107]
	v_mfma_f32_16x16x32_bf16 v[96:99], v[146:149], v[186:189], v[96:99]
	v_mfma_f32_16x16x32_bf16 v[88:91], v[138:141], v[194:197], v[88:91]
	v_mfma_f32_16x16x32_bf16 v[80:83], v[146:149], v[194:197], v[80:83]
	v_mfma_f32_16x16x32_bf16 v[124:127], v[142:145], v[170:173], v[124:127]
	v_mfma_f32_16x16x32_bf16 v[120:123], v[162:165], v[170:173], v[120:123]
	v_mfma_f32_16x16x32_bf16 v[116:119], v[142:145], v[178:181], v[116:119]
	v_mfma_f32_16x16x32_bf16 v[112:115], v[162:165], v[178:181], v[112:115]
	v_mfma_f32_16x16x32_bf16 v[104:107], v[142:145], v[190:193], v[104:107]
	v_mfma_f32_16x16x32_bf16 v[96:99], v[162:165], v[190:193], v[96:99]
	v_mfma_f32_16x16x32_bf16 v[88:91], v[142:145], v[198:201], v[88:91]
	v_mfma_f32_16x16x32_bf16 v[80:83], v[162:165], v[198:201], v[80:83]
	s_barrier
	s_add_i32 s69, s47, s36
	v_lshl_add_u64 v[150:151], s[24:25], 0, v[128:129]
	s_mov_b32 m0, s69
	ds_read_b128 v[202:205], v157
	ds_read_b128 v[206:209], v157 offset:1024
	ds_read_b128 v[210:213], v157 offset:2048
	ds_read_b128 v[214:217], v157 offset:3072
	global_load_lds_dwordx4 v[150:151], off
	v_lshl_add_u64 v[158:159], s[24:25], 0, v[130:131]
	s_add_i32 m0, s69, 0x2000
	s_nop 0
	global_load_lds_dwordx4 v[158:159], off
	s_barrier
; #define PG8_STAGE(bufoff, gbase, voff) do { _Pragma("unroll") for (int _i = 0; _i < 2; ++_i) \
;         __builtin_amdgcn_global_load_lds((const unsigned*)((const char*)(gbase) + (voff)[_i]), (LAS unsigned*)(lds + (bufoff) + ldsw + _i * 8192), 16, 0, 0); } while (0)
; #define PG8_LDA(dst, b, h) do { _Pragma("unroll") for (int m = 0; m < 4; ++m) _Pragma("unroll") for (int k = 0; k < 2; ++k) dst[m][k] = *(const LAS bf16x8*)(lds + PG8_SA(b, h) + aoff + m * 2048 + k * 1024); } while (0)
; #define PG8_LDB(dst, b, h) do { _Pragma("unroll") for (int n = 0; n < 2; ++n) _Pragma("unroll") for (int k = 0; k < 2; ++k) dst[n][k] = *(const LAS bf16x8*)(lds + PG8_SB(b, h) + boff + n * 2048 + k * 1024); } while (0)
; #define PG8_MMA(ai, bj, At, Bt) do { __builtin_amdgcn_s_setprio(1); _Pragma("unroll") for (int m = 0; m < 4; ++m) _Pragma("unroll") for (int n = 0; n < 2; ++n) _Pragma("unroll") for (int k = 0; k < 2; ++k) \
;         acc[ai][bj][m][n] = __builtin_amdgcn_mfma_f32_16x16x32_bf16(Bt[n][k], At[m][k], acc[ai][bj][m][n], 0, 0, 0); __builtin_amdgcn_s_setprio(0); } while (0)
; #define PG8_WAIT_V(n) asm volatile("s_waitcnt vmcnt(" #n ")" ::: "memory")
; #define PG8_WAIT_L(n) asm volatile("s_waitcnt lgkmcnt(" #n ")" ::: "memory")
; #define PG8_BAR __builtin_amdgcn_s_barrier()
; #define PG8_SCHED __builtin_amdgcn_sched_barrier(0)
; template <class Epi, class Sched>
; __device__ __forceinline__ void gemm_phase(LAS unsigned char* lds, const Gemm g, const Sched& S, const Epi& E) {
;     ...
;             PG8_BAR; PG8_WAIT_L(0); if constexpr (!Epi::DIAG) PG8_MMA(0, 1, At, B1); PG8_BAR;
;             PG8_LDA(At, 0, 1); PG8_STAGE(PG8_SA(0, 0), a2, voffA);
;             PG8_BAR; PG8_WAIT_L(0); if constexpr (!Epi::DIAG) PG8_MMA(1, 0, At, B0); PG8_BAR; PG8_SCHED;
;             PG8_STAGE(PG8_SB(0, 1), b2 + hstepB, voffB);
;             PG8_WAIT_V(6); PG8_BAR; PG8_MMA(1, 1, At, B1); PG8_BAR;
;             PG8_LDB(B0, 1, 0); PG8_SCHED; PG8_LDA(At, 1, 0); PG8_STAGE(PG8_SA(0, 1), a2 + hstepA, voffA);
;             PG8_WAIT_L(8); PG8_BAR; PG8_WAIT_L(0); PG8_MMA(0, 0, At, B0); PG8_BAR; PG8_SCHED;
	s_waitcnt lgkmcnt(0)
	s_waitcnt lgkmcnt(0)
	v_mfma_f32_16x16x32_bf16 v[108:111], v[202:205], v[166:169], v[108:111]
	v_mfma_f32_16x16x32_bf16 v[100:103], v[210:213], v[166:169], v[100:103]
	v_mfma_f32_16x16x32_bf16 v[92:95], v[202:205], v[174:177], v[92:95]
	v_mfma_f32_16x16x32_bf16 v[84:87], v[210:213], v[174:177], v[84:87]
	v_mfma_f32_16x16x32_bf16 v[76:79], v[202:205], v[186:189], v[76:79]
	v_mfma_f32_16x16x32_bf16 v[72:75], v[210:213], v[186:189], v[72:75]
	v_mfma_f32_16x16x32_bf16 v[68:71], v[202:205], v[194:197], v[68:71]
	v_mfma_f32_16x16x32_bf16 v[64:67], v[210:213], v[194:197], v[64:67]
	v_mfma_f32_16x16x32_bf16 v[108:111], v[206:209], v[170:173], v[108:111]
	v_mfma_f32_16x16x32_bf16 v[100:103], v[214:217], v[170:173], v[100:103]
	v_mfma_f32_16x16x32_bf16 v[92:95], v[206:209], v[178:181], v[92:95]
	v_mfma_f32_16x16x32_bf16 v[84:87], v[214:217], v[178:181], v[84:87]
	v_mfma_f32_16x16x32_bf16 v[76:79], v[206:209], v[190:193], v[76:79]
	v_mfma_f32_16x16x32_bf16 v[72:75], v[214:217], v[190:193], v[72:75]
	v_mfma_f32_16x16x32_bf16 v[68:71], v[206:209], v[198:201], v[68:71]
	v_mfma_f32_16x16x32_bf16 v[64:67], v[214:217], v[198:201], v[64:67]
	s_mov_b32 m0, s37
	v_lshl_add_u64 v[182:183], s[26:27], 0, v[128:129]
	s_barrier
	ds_read_b128 v[166:169], v156 offset:16384
	ds_read_b128 v[170:173], v156 offset:17408
	ds_read_b128 v[174:177], v156 offset:18432
	ds_read_b128 v[178:181], v156 offset:19456
	ds_read_b128 v[186:189], v156 offset:20480
	ds_read_b128 v[190:193], v156 offset:21504
	ds_read_b128 v[194:197], v156 offset:22528
	ds_read_b128 v[198:201], v156 offset:23552
	global_load_lds_dwordx4 v[182:183], off
	v_lshl_add_u64 v[218:219], s[26:27], 0, v[130:131]
	s_mov_b32 m0, s38
	s_nop 0
	global_load_lds_dwordx4 v[218:219], off
	s_barrier
	s_waitcnt lgkmcnt(0)
	s_waitcnt lgkmcnt(0)
	v_mfma_f32_16x16x32_bf16 v[60:63], v[138:141], v[166:169], v[60:63]
	v_mfma_f32_16x16x32_bf16 v[56:59], v[146:149], v[166:169], v[56:59]
	v_mfma_f32_16x16x32_bf16 v[52:55], v[138:141], v[174:177], v[52:55]
	v_mfma_f32_16x16x32_bf16 v[48:51], v[146:149], v[174:177], v[48:51]
	v_mfma_f32_16x16x32_bf16 v[40:43], v[138:141], v[186:189], v[40:43]
	v_mfma_f32_16x16x32_bf16 v[32:35], v[146:149], v[186:189], v[32:35]
	v_mfma_f32_16x16x32_bf16 v[24:27], v[138:141], v[194:197], v[24:27]
	v_mfma_f32_16x16x32_bf16 v[16:19], v[146:149], v[194:197], v[16:19]
	v_mfma_f32_16x16x32_bf16 v[60:63], v[142:145], v[170:173], v[60:63]
	v_mfma_f32_16x16x32_bf16 v[56:59], v[162:165], v[170:173], v[56:59]
	v_mfma_f32_16x16x32_bf16 v[52:55], v[142:145], v[178:181], v[52:55]
	v_mfma_f32_16x16x32_bf16 v[48:51], v[162:165], v[178:181], v[48:51]
	v_mfma_f32_16x16x32_bf16 v[40:43], v[142:145], v[190:193], v[40:43]
	v_mfma_f32_16x16x32_bf16 v[32:35], v[162:165], v[190:193], v[32:35]
	v_mfma_f32_16x16x32_bf16 v[24:27], v[142:145], v[198:201], v[24:27]
	v_mfma_f32_16x16x32_bf16 v[16:19], v[162:165], v[198:201], v[16:19]
	s_barrier
	s_add_u32 s70, s24, 0x160000
	s_addc_u32 s71, s25, 0
	s_add_i32 s69, s49, s36
	v_lshl_add_u64 v[138:139], s[70:71], 0, v[128:129]
	s_mov_b32 m0, s69
	s_nop 0
	global_load_lds_dwordx4 v[138:139], off
	v_lshl_add_u64 v[138:139], s[70:71], 0, v[130:131]
	s_add_i32 m0, s69, 0x2000
	s_nop 0
	global_load_lds_dwordx4 v[138:139], off
	s_waitcnt vmcnt(6)
	s_barrier
	v_mfma_f32_16x16x32_bf16 v[44:47], v[202:205], v[166:169], v[44:47]
	v_mfma_f32_16x16x32_bf16 v[36:39], v[210:213], v[166:169], v[36:39]
	v_mfma_f32_16x16x32_bf16 v[28:31], v[202:205], v[174:177], v[28:31]
	v_mfma_f32_16x16x32_bf16 v[20:23], v[210:213], v[174:177], v[20:23]
	v_mfma_f32_16x16x32_bf16 v[12:15], v[202:205], v[186:189], v[12:15]
	v_mfma_f32_16x16x32_bf16 v[8:11], v[210:213], v[186:189], v[8:11]
	v_mfma_f32_16x16x32_bf16 v[4:7], v[202:205], v[194:197], v[4:7]
	v_mfma_f32_16x16x32_bf16 v[0:3], v[210:213], v[194:197], v[0:3]
	v_mfma_f32_16x16x32_bf16 v[44:47], v[206:209], v[170:173], v[44:47]
	v_mfma_f32_16x16x32_bf16 v[36:39], v[214:217], v[170:173], v[36:39]
	v_mfma_f32_16x16x32_bf16 v[28:31], v[206:209], v[178:181], v[28:31]
	v_mfma_f32_16x16x32_bf16 v[20:23], v[214:217], v[178:181], v[20:23]
	v_mfma_f32_16x16x32_bf16 v[12:15], v[206:209], v[190:193], v[12:15]
	v_mfma_f32_16x16x32_bf16 v[8:11], v[214:217], v[190:193], v[8:11]
	v_mfma_f32_16x16x32_bf16 v[4:7], v[206:209], v[198:201], v[4:7]
	v_mfma_f32_16x16x32_bf16 v[0:3], v[214:217], v[198:201], v[0:3]
	s_add_i32 s69, 0, 0x18000
	v_add_u32_e32 v132, s69, v153
	s_barrier
	ds_read_b128 v[138:141], v132
	ds_read_b128 v[142:145], v132 offset:1024
	ds_read_b128 v[146:149], v132 offset:2048
	ds_read_b128 v[162:165], v132 offset:3072
	s_add_u32 s26, s26, 0x160000
	s_addc_u32 s27, s27, 0
	s_mov_b32 m0, s39
	v_lshl_add_u64 v[202:203], s[26:27], 0, v[128:129]
	ds_read_b128 v[166:169], v156 offset:32768
	ds_read_b128 v[170:173], v156 offset:33792
	ds_read_b128 v[174:177], v156 offset:34816
	ds_read_b128 v[178:181], v156 offset:35840
	ds_read_b128 v[186:189], v156 offset:36864
	ds_read_b128 v[190:193], v156 offset:37888
	ds_read_b128 v[194:197], v156 offset:38912
	ds_read_b128 v[198:201], v156 offset:39936
	global_load_lds_dwordx4 v[202:203], off
	v_lshl_add_u64 v[202:203], s[26:27], 0, v[130:131]
	s_mov_b32 m0, s40
	s_nop 0
	global_load_lds_dwordx4 v[202:203], off
	s_waitcnt lgkmcnt(8)
	s_barrier
; #define PG8_STAGE(bufoff, gbase, voff) do { _Pragma("unroll") for (int _i = 0; _i < 2; ++_i) \
;         __builtin_amdgcn_global_load_lds((const unsigned*)((const char*)(gbase) + (voff)[_i]), (LAS unsigned*)(lds + (bufoff) + ldsw + _i * 8192), 16, 0, 0); } while (0)
; #define PG8_LDA(dst, b, h) do { _Pragma("unroll") for (int m = 0; m < 4; ++m) _Pragma("unroll") for (int k = 0; k < 2; ++k) dst[m][k] = *(const LAS bf16x8*)(lds + PG8_SA(b, h) + aoff + m * 2048 + k * 1024); } while (0)
; #define PG8_LDB(dst, b, h) do { _Pragma("unroll") for (int n = 0; n < 2; ++n) _Pragma("unroll") for (int k = 0; k < 2; ++k) dst[n][k] = *(const LAS bf16x8*)(lds + PG8_SB(b, h) + boff + n * 2048 + k * 1024); } while (0)
; #define PG8_MMA(ai, bj, At, Bt) do { __builtin_amdgcn_s_setprio(1); _Pragma("unroll") for (int m = 0; m < 4; ++m) _Pragma("unroll") for (int n = 0; n < 2; ++n) _Pragma("unroll") for (int k = 0; k < 2; ++k) \
;         acc[ai][bj][m][n] = __builtin_amdgcn_mfma_f32_16x16x32_bf16(Bt[n][k], At[m][k], acc[ai][bj][m][n], 0, 0, 0); __builtin_amdgcn_s_setprio(0); } while (0)
; #define PG8_WAIT_V(n) asm volatile("s_waitcnt vmcnt(" #n ")" ::: "memory")
; #define PG8_WAIT_L(n) asm volatile("s_waitcnt lgkmcnt(" #n ")" ::: "memory")
; #define PG8_BAR __builtin_amdgcn_s_barrier()
; #define PG8_SCHED __builtin_amdgcn_sched_barrier(0)
; template <class Epi, class Sched>
; __device__ __forceinline__ void gemm_phase(LAS unsigned char* lds, const Gemm g, const Sched& S, const Epi& E) {
;     ...
;             PG8_WAIT_L(8); PG8_BAR; PG8_WAIT_L(0); PG8_MMA(0, 0, At, B0); PG8_BAR; PG8_SCHED;
;             PG8_LDB(B1, 1, 1); PG8_STAGE(PG8_SB(1, 0), b3, voffB);
;             PG8_BAR; PG8_WAIT_L(0); if constexpr (!Epi::DIAG) PG8_MMA(0, 1, At, B1); PG8_BAR;
;             PG8_LDA(At, 1, 1); PG8_STAGE(PG8_SA(1, 0), a3, voffA);
;             PG8_BAR; PG8_WAIT_L(0); if constexpr (!Epi::DIAG) PG8_MMA(1, 0, At, B0); PG8_BAR; PG8_SCHED;
;             PG8_STAGE(PG8_SB(1, 1), b3 + hstepB, voffB);
;             PG8_WAIT_V(6); PG8_BAR; PG8_MMA(1, 1, At, B1); PG8_BAR;
	s_waitcnt lgkmcnt(0)
	s_waitcnt lgkmcnt(0)
	v_mfma_f32_16x16x32_bf16 v[124:127], v[138:141], v[166:169], v[124:127]
	v_mfma_f32_16x16x32_bf16 v[120:123], v[146:149], v[166:169], v[120:123]
	v_mfma_f32_16x16x32_bf16 v[116:119], v[138:141], v[174:177], v[116:119]
	v_mfma_f32_16x16x32_bf16 v[112:115], v[146:149], v[174:177], v[112:115]
	v_mfma_f32_16x16x32_bf16 v[104:107], v[138:141], v[186:189], v[104:107]
	v_mfma_f32_16x16x32_bf16 v[96:99], v[146:149], v[186:189], v[96:99]
	v_mfma_f32_16x16x32_bf16 v[88:91], v[138:141], v[194:197], v[88:91]
	v_mfma_f32_16x16x32_bf16 v[80:83], v[146:149], v[194:197], v[80:83]
	v_mfma_f32_16x16x32_bf16 v[124:127], v[142:145], v[170:173], v[124:127]
	v_mfma_f32_16x16x32_bf16 v[120:123], v[162:165], v[170:173], v[120:123]
	v_mfma_f32_16x16x32_bf16 v[116:119], v[142:145], v[178:181], v[116:119]
	v_mfma_f32_16x16x32_bf16 v[112:115], v[162:165], v[178:181], v[112:115]
	v_mfma_f32_16x16x32_bf16 v[104:107], v[142:145], v[190:193], v[104:107]
	v_mfma_f32_16x16x32_bf16 v[96:99], v[162:165], v[190:193], v[96:99]
	v_mfma_f32_16x16x32_bf16 v[88:91], v[142:145], v[198:201], v[88:91]
	v_mfma_f32_16x16x32_bf16 v[80:83], v[162:165], v[198:201], v[80:83]
	s_barrier
	s_add_i32 s26, 0, 0x1c000
	s_add_i32 s27, s69, s36
	v_add_u32_e32 v132, s26, v153
	v_lshl_add_u64 v[150:151], v[150:151], 0, s[16:17]
	s_mov_b32 m0, s27
	ds_read_b128 v[202:205], v132
	ds_read_b128 v[206:209], v132 offset:1024
	ds_read_b128 v[210:213], v132 offset:2048
	ds_read_b128 v[214:217], v132 offset:3072
	global_load_lds_dwordx4 v[150:151], off
	v_lshl_add_u64 v[150:151], v[158:159], 0, s[16:17]
	s_add_i32 m0, s27, 0x2000
	s_nop 0
	global_load_lds_dwordx4 v[150:151], off
	s_barrier
	s_waitcnt lgkmcnt(0)
	s_waitcnt lgkmcnt(0)
	v_mfma_f32_16x16x32_bf16 v[108:111], v[202:205], v[166:169], v[108:111]
	v_mfma_f32_16x16x32_bf16 v[100:103], v[210:213], v[166:169], v[100:103]
	v_mfma_f32_16x16x32_bf16 v[92:95], v[202:205], v[174:177], v[92:95]
	v_mfma_f32_16x16x32_bf16 v[84:87], v[210:213], v[174:177], v[84:87]
	v_mfma_f32_16x16x32_bf16 v[76:79], v[202:205], v[186:189], v[76:79]
	v_mfma_f32_16x16x32_bf16 v[72:75], v[210:213], v[186:189], v[72:75]
	v_mfma_f32_16x16x32_bf16 v[68:71], v[202:205], v[194:197], v[68:71]
	v_mfma_f32_16x16x32_bf16 v[64:67], v[210:213], v[194:197], v[64:67]
	v_mfma_f32_16x16x32_bf16 v[108:111], v[206:209], v[170:173], v[108:111]
	v_mfma_f32_16x16x32_bf16 v[100:103], v[214:217], v[170:173], v[100:103]
	v_mfma_f32_16x16x32_bf16 v[92:95], v[206:209], v[178:181], v[92:95]
	v_mfma_f32_16x16x32_bf16 v[84:87], v[214:217], v[178:181], v[84:87]
	v_mfma_f32_16x16x32_bf16 v[76:79], v[206:209], v[190:193], v[76:79]
	v_mfma_f32_16x16x32_bf16 v[72:75], v[214:217], v[190:193], v[72:75]
	v_mfma_f32_16x16x32_bf16 v[68:71], v[206:209], v[198:201], v[68:71]
	v_mfma_f32_16x16x32_bf16 v[64:67], v[214:217], v[198:201], v[64:67]
	s_mov_b32 m0, s45
	v_lshl_add_u64 v[150:151], v[182:183], 0, s[16:17]
	s_barrier
	ds_read_b128 v[166:169], v156 offset:49152
	ds_read_b128 v[170:173], v156 offset:50176
	ds_read_b128 v[174:177], v156 offset:51200
	ds_read_b128 v[178:181], v156 offset:52224
	ds_read_b128 v[186:189], v156 offset:53248
	ds_read_b128 v[190:193], v156 offset:54272
	ds_read_b128 v[194:197], v156 offset:55296
	ds_read_b128 v[198:201], v156 offset:56320
	global_load_lds_dwordx4 v[150:151], off
	v_lshl_add_u64 v[150:151], v[218:219], 0, s[16:17]
	s_mov_b32 m0, s46
	s_nop 0
	global_load_lds_dwordx4 v[150:151], off
	s_barrier
	s_waitcnt lgkmcnt(0)
	s_waitcnt lgkmcnt(0)
	v_mfma_f32_16x16x32_bf16 v[60:63], v[138:141], v[166:169], v[60:63]
	v_mfma_f32_16x16x32_bf16 v[56:59], v[146:149], v[166:169], v[56:59]
	v_mfma_f32_16x16x32_bf16 v[52:55], v[138:141], v[174:177], v[52:55]
	v_mfma_f32_16x16x32_bf16 v[48:51], v[146:149], v[174:177], v[48:51]
	v_mfma_f32_16x16x32_bf16 v[40:43], v[138:141], v[186:189], v[40:43]
	v_mfma_f32_16x16x32_bf16 v[32:35], v[146:149], v[186:189], v[32:35]
	v_mfma_f32_16x16x32_bf16 v[24:27], v[138:141], v[194:197], v[24:27]
	v_mfma_f32_16x16x32_bf16 v[16:19], v[146:149], v[194:197], v[16:19]
	v_mfma_f32_16x16x32_bf16 v[60:63], v[142:145], v[170:173], v[60:63]
	v_mfma_f32_16x16x32_bf16 v[56:59], v[162:165], v[170:173], v[56:59]
	v_mfma_f32_16x16x32_bf16 v[52:55], v[142:145], v[178:181], v[52:55]
	v_mfma_f32_16x16x32_bf16 v[48:51], v[162:165], v[178:181], v[48:51]
	v_mfma_f32_16x16x32_bf16 v[40:43], v[142:145], v[190:193], v[40:43]
	v_mfma_f32_16x16x32_bf16 v[32:35], v[162:165], v[190:193], v[32:35]
	v_mfma_f32_16x16x32_bf16 v[24:27], v[142:145], v[198:201], v[24:27]
	v_mfma_f32_16x16x32_bf16 v[16:19], v[162:165], v[198:201], v[16:19]
	s_barrier
	s_add_u32 s24, s24, 0x160080
	s_addc_u32 s25, s25, 0
	s_add_i32 s26, s26, s36
	v_lshl_add_u64 v[138:139], s[24:25], 0, v[128:129]
	s_mov_b32 m0, s26
	s_nop 0
	global_load_lds_dwordx4 v[138:139], off
	v_lshl_add_u64 v[138:139], s[24:25], 0, v[130:131]
	s_add_i32 m0, s26, 0x2000
	s_nop 0
	global_load_lds_dwordx4 v[138:139], off
	s_waitcnt vmcnt(6)
	s_barrier
	v_mfma_f32_16x16x32_bf16 v[44:47], v[202:205], v[166:169], v[44:47]
	v_mfma_f32_16x16x32_bf16 v[36:39], v[210:213], v[166:169], v[36:39]
	v_mfma_f32_16x16x32_bf16 v[28:31], v[202:205], v[174:177], v[28:31]
	v_mfma_f32_16x16x32_bf16 v[20:23], v[210:213], v[174:177], v[20:23]
	v_mfma_f32_16x16x32_bf16 v[12:15], v[202:205], v[186:189], v[12:15]
	v_mfma_f32_16x16x32_bf16 v[8:11], v[210:213], v[186:189], v[8:11]
	v_mfma_f32_16x16x32_bf16 v[4:7], v[202:205], v[194:197], v[4:7]
	v_mfma_f32_16x16x32_bf16 v[0:3], v[210:213], v[194:197], v[0:3]
	v_mfma_f32_16x16x32_bf16 v[44:47], v[206:209], v[170:173], v[44:47]
	v_mfma_f32_16x16x32_bf16 v[36:39], v[214:217], v[170:173], v[36:39]
	v_mfma_f32_16x16x32_bf16 v[28:31], v[206:209], v[178:181], v[28:31]
	v_mfma_f32_16x16x32_bf16 v[20:23], v[214:217], v[178:181], v[20:23]
	v_mfma_f32_16x16x32_bf16 v[12:15], v[206:209], v[190:193], v[12:15]
	v_mfma_f32_16x16x32_bf16 v[8:11], v[214:217], v[190:193], v[8:11]
	v_mfma_f32_16x16x32_bf16 v[4:7], v[206:209], v[198:201], v[4:7]
	v_mfma_f32_16x16x32_bf16 v[0:3], v[214:217], v[198:201], v[0:3]
	s_add_u32 s6, s6, 0x100
	s_addc_u32 s7, s7, 0
	s_add_u32 s29, s29, 0x100
	s_addc_u32 s67, s67, 0
	s_cmp_ge_u32 s68, s66
	s_mov_b32 s24, s68
	s_barrier
; #define PG8_MMA(ai, bj, At, Bt) do { __builtin_amdgcn_s_setprio(1); _Pragma("unroll") for (int m = 0; m < 4; ++m) _Pragma("unroll") for (int n = 0; n < 2; ++n) _Pragma("unroll") for (int k = 0; k < 2; ++k) \
;         acc[ai][bj][m][n] = __builtin_amdgcn_mfma_f32_16x16x32_bf16(Bt[n][k], At[m][k], acc[ai][bj][m][n], 0, 0, 0); __builtin_amdgcn_s_setprio(0); } while (0)
; #define PG8_WAIT_V(n) asm volatile("s_waitcnt vmcnt(" #n ")" ::: "memory")
; #define PG8_BAR __builtin_amdgcn_s_barrier()
; template <class Epi, class Sched>
; __device__ __forceinline__ void gemm_phase(LAS unsigned char* lds, const Gemm g, const Sched& S, const Epi& E) {
;     ...
;             PG8_WAIT_V(6); PG8_BAR; PG8_MMA(1, 1, At, B1); PG8_BAR;
;         }
;         E(acc, cur, wr, wc, fr, fq);
;     __device__ __forceinline__ void operator()(const Acc& acc, const Unit& u, int wr, int wc, int fr, int fq) const {
;         const int row0 = u.pm * BM + wr * 64 + fr, col0 = u.pn * BM + wc * 32 + 4 * fq;
;         if (u.piece >= 0) {
;             float* pb = PB + (size_t)u.piece * TS * DM;
; #pragma unroll
;             for (int ai = 0; ai < 2; ++ai)
; #pragma unroll
;                 for (int m = 0; m < 4; ++m) { float* orow = pb + (size_t)(row0 + ai * HALF + m * 16 - TP) * DM;
; #pragma unroll
;                     for (int bj = 0; bj < 2; ++bj)
; #pragma unroll
;                         for (int n = 0; n < 2; ++n) *(f32x4*)(orow + col0 + bj * HALF + n * 16) = acc[ai][bj][m][n]; }
;             return;
;         }
; #pragma unroll
;         for (int ai = 0; ai < 2; ++ai)
; #pragma unroll
;             for (int m = 0; m < 4; ++m) { const int row = row0 + ai * HALF + m * 16; const int b = bidx_of_row(row);
;                 const float* xr = (row < TP) ? x0p + (size_t)row * DM : x0s + (size_t)(row - TP) * DM; const float* gr = gate + (size_t)b * MODW; float* orow = X1 + (size_t)row * DM;
; #pragma unroll
;                 for (int bj = 0; bj < 2; ++bj)
; #pragma unroll
;                     for (int n = 0; n < 2; ++n) { const int c = col0 + bj * HALF + n * 16; const f32x4 xv = *(const f32x4*)(xr + c), gv = *(const f32x4*)(gr + c);
;                         *(f32x4*)(orow + c) = xv + gv * acc[ai][bj][m][n]; } }
	s_cbranch_scc0 .LBB0_1915
	s_setprio 0
	s_lshl_b32 s24, s65, 8
	s_add_i32 s24, s24, s44
	v_or_b32_e32 v138, s24, v152
	v_lshl_or_b32 v142, s64, 8, v154
	s_cmp_gt_i32 s8, -1
	v_add_u32_e32 v140, 0xffffe000, v138
	s_mov_b64 s[6:7], -1
	s_cbranch_scc1 .LBB0_1950
	v_cmp_gt_i32_e32 vcc, s41, v138
	v_cmp_lt_i32_e64 s[6:7], s50, v138
	s_and_saveexec_b64 s[26:27], s[6:7]
	s_xor_b64 s[6:7], exec, s[26:27]
	v_mov_b32_e32 v141, v133
	v_lshlrev_b64 v[144:145], 13, v[140:141]
	v_mov_b32_e32 v139, v133
	v_lshl_add_u64 v[148:149], s[12:13], 0, v[144:145]
	v_lshlrev_b64 v[146:147], 13, v[138:139]
	s_andn2_saveexec_b64 s[6:7], s[6:7]
	v_ashrrev_i32_e32 v139, 31, v138
	v_lshlrev_b64 v[146:147], 13, v[138:139]
	v_lshl_add_u64 v[148:149], s[10:11], 0, v[146:147]
	s_or_b64 exec, exec, s[6:7]
	s_ashr_i32 s24, s24, 11
	v_lshrrev_b32_e32 v132, 2, v140
	v_or_b32_e32 v132, 4, v132
	v_mov_b32_e32 v139, s24
	v_cndmask_b32_e32 v132, v132, v139, vcc
	v_mov_b64_e32 v[144:145], s[14:15]
	v_ashrrev_i32_e32 v143, 31, v142
	v_mad_i64_i32 v[158:159], s[6:7], v132, s48, v[144:145]
	v_lshlrev_b64 v[144:145], 2, v[142:143]
	v_lshl_add_u64 v[166:167], v[148:149], 0, v[144:145]
	v_lshl_add_u64 v[158:159], v[158:159], 0, v[144:145]
	global_load_dwordx4 v[186:189], v[166:167], off
	global_load_dwordx4 v[202:205], v[158:159], off
	global_load_dwordx4 v[190:193], v[166:167], off offset:64
	global_load_dwordx4 v[206:209], v[158:159], off offset:64
	global_load_dwordx4 v[194:197], v[166:167], off offset:512
	global_load_dwordx4 v[210:213], v[158:159], off offset:512
	global_load_dwordx4 v[198:201], v[166:167], off offset:576
	global_load_dwordx4 v[214:217], v[158:159], off offset:576
	v_lshl_add_u64 v[146:147], s[10:11], 0, v[146:147]
	v_lshl_add_u64 v[168:169], v[146:147], 0, v[144:145]
	v_add_u32_e32 v132, 0xffffe010, v138
	s_waitcnt vmcnt(6)
	v_pk_fma_f32 v[188:189], v[126:127], v[204:205], v[188:189]
	v_pk_fma_f32 v[186:187], v[124:125], v[202:203], v[186:187]
	global_store_dwordx4 v[168:169], v[186:189], off
	v_or_b32_e32 v150, 16, v138
	v_cmp_gt_i32_e32 vcc, s41, v150
	v_cmp_lt_i32_e64 s[6:7], s50, v150
	s_waitcnt vmcnt(5)
	v_pk_fma_f32 v[192:193], v[122:123], v[208:209], v[192:193]
	v_pk_fma_f32 v[190:191], v[120:121], v[206:207], v[190:191]
	global_store_dwordx4 v[168:169], v[190:193], off offset:64
	s_waitcnt vmcnt(4)
	v_pk_fma_f32 v[196:197], v[110:111], v[212:213], v[196:197]
	v_pk_fma_f32 v[194:195], v[108:109], v[210:211], v[194:195]
	global_store_dwordx4 v[168:169], v[194:197], off offset:512
	s_waitcnt vmcnt(3)
	v_pk_fma_f32 v[200:201], v[102:103], v[216:217], v[200:201]
	v_pk_fma_f32 v[198:199], v[100:101], v[214:215], v[198:199]
	global_store_dwordx4 v[168:169], v[198:201], off offset:576
	s_and_saveexec_b64 s[26:27], s[6:7]
	s_xor_b64 s[6:7], exec, s[26:27]
	v_lshlrev_b64 v[146:147], 13, v[132:133]
	v_mov_b32_e32 v151, v133
	v_lshl_add_u64 v[148:149], s[12:13], 0, v[146:147]
	v_lshlrev_b64 v[146:147], 13, v[150:151]
	s_andn2_saveexec_b64 s[6:7], s[6:7]
	v_ashrrev_i32_e32 v151, 31, v150
	v_lshlrev_b64 v[146:147], 13, v[150:151]
	v_lshl_add_u64 v[148:149], s[10:11], 0, v[146:147]
	s_or_b64 exec, exec, s[6:7]
	v_lshrrev_b32_e32 v132, 2, v132
	v_add_u32_e32 v132, 4, v132
	v_mov_b32_e32 v139, s24
	v_cndmask_b32_e32 v132, v132, v139, vcc
	v_mov_b64_e32 v[150:151], s[14:15]
	v_mad_i64_i32 v[158:159], s[6:7], v132, s48, v[150:151]
	v_lshl_add_u64 v[166:167], v[148:149], 0, v[144:145]
	v_lshl_add_u64 v[158:159], v[158:159], 0, v[144:145]
	global_load_dwordx4 v[186:189], v[166:167], off
	global_load_dwordx4 v[202:205], v[158:159], off
	global_load_dwordx4 v[190:193], v[166:167], off offset:64
	global_load_dwordx4 v[206:209], v[158:159], off offset:64
	global_load_dwordx4 v[194:197], v[166:167], off offset:512
	global_load_dwordx4 v[210:213], v[158:159], off offset:512
	global_load_dwordx4 v[198:201], v[166:167], off offset:576
	global_load_dwordx4 v[214:217], v[158:159], off offset:576
	v_lshl_add_u64 v[146:147], s[10:11], 0, v[146:147]
	v_lshl_add_u64 v[168:169], v[146:147], 0, v[144:145]
	v_add_u32_e32 v132, 0xffffe020, v138
	s_waitcnt vmcnt(6)
	v_pk_fma_f32 v[188:189], v[118:119], v[204:205], v[188:189]
	v_pk_fma_f32 v[186:187], v[116:117], v[202:203], v[186:187]
	global_store_dwordx4 v[168:169], v[186:189], off
	v_or_b32_e32 v150, 32, v138
	v_cmp_gt_i32_e32 vcc, s41, v150
	v_cmp_lt_i32_e64 s[6:7], s50, v150
	s_waitcnt vmcnt(5)
	v_pk_fma_f32 v[192:193], v[114:115], v[208:209], v[192:193]
	v_pk_fma_f32 v[190:191], v[112:113], v[206:207], v[190:191]
	global_store_dwordx4 v[168:169], v[190:193], off offset:64
	s_waitcnt vmcnt(4)
	v_pk_fma_f32 v[196:197], v[94:95], v[212:213], v[196:197]
	v_pk_fma_f32 v[194:195], v[92:93], v[210:211], v[194:195]
	global_store_dwordx4 v[168:169], v[194:197], off offset:512
	s_waitcnt vmcnt(3)
	v_pk_fma_f32 v[200:201], v[86:87], v[216:217], v[200:201]
	v_pk_fma_f32 v[198:199], v[84:85], v[214:215], v[198:199]
	global_store_dwordx4 v[168:169], v[198:201], off offset:576
	s_and_saveexec_b64 s[26:27], s[6:7]
	s_xor_b64 s[6:7], exec, s[26:27]
	v_lshlrev_b64 v[146:147], 13, v[132:133]
	v_mov_b32_e32 v151, v133
	v_lshl_add_u64 v[148:149], s[12:13], 0, v[146:147]
	v_lshlrev_b64 v[146:147], 13, v[150:151]
	s_andn2_saveexec_b64 s[6:7], s[6:7]
	v_ashrrev_i32_e32 v151, 31, v150
	v_lshlrev_b64 v[146:147], 13, v[150:151]
	v_lshl_add_u64 v[148:149], s[10:11], 0, v[146:147]
	s_or_b64 exec, exec, s[6:7]
	v_lshrrev_b32_e32 v132, 2, v132
	v_or_b32_e32 v132, 4, v132
	v_mov_b32_e32 v139, s24
	v_cndmask_b32_e32 v132, v132, v139, vcc
	v_mov_b64_e32 v[150:151], s[14:15]
	v_mad_i64_i32 v[158:159], s[6:7], v132, s48, v[150:151]
	v_lshl_add_u64 v[166:167], v[148:149], 0, v[144:145]
	v_lshl_add_u64 v[158:159], v[158:159], 0, v[144:145]
	global_load_dwordx4 v[186:189], v[166:167], off
	global_load_dwordx4 v[202:205], v[158:159], off
	global_load_dwordx4 v[190:193], v[166:167], off offset:64
	global_load_dwordx4 v[206:209], v[158:159], off offset:64
	global_load_dwordx4 v[194:197], v[166:167], off offset:512
	global_load_dwordx4 v[210:213], v[158:159], off offset:512
	global_load_dwordx4 v[198:201], v[166:167], off offset:576
	global_load_dwordx4 v[214:217], v[158:159], off offset:576
	v_lshl_add_u64 v[146:147], s[10:11], 0, v[146:147]
	v_lshl_add_u64 v[168:169], v[146:147], 0, v[144:145]
	v_add_u32_e32 v132, 0xffffe030, v138
	s_waitcnt vmcnt(6)
;     __device__ __forceinline__ void operator()(const Acc& acc, const Unit& u, int wr, int wc, int fr, int fq) const {
;     ...
;         for (int ai = 0; ai < 2; ++ai)
; #pragma unroll
;             for (int m = 0; m < 4; ++m) { const int row = row0 + ai * HALF + m * 16; const int b = bidx_of_row(row);
;                 const float* xr = (row < TP) ? x0p + (size_t)row * DM : x0s + (size_t)(row - TP) * DM; const float* gr = gate + (size_t)b * MODW; float* orow = X1 + (size_t)row * DM;
; #pragma unroll
;                 for (int bj = 0; bj < 2; ++bj)
; #pragma unroll
;                     for (int n = 0; n < 2; ++n) { const int c = col0 + bj * HALF + n * 16; const f32x4 xv = *(const f32x4*)(xr + c), gv = *(const f32x4*)(gr + c);
;                         *(f32x4*)(orow + c) = xv + gv * acc[ai][bj][m][n]; } }
	v_pk_fma_f32 v[188:189], v[106:107], v[204:205], v[188:189]
	v_pk_fma_f32 v[186:187], v[104:105], v[202:203], v[186:187]
	global_store_dwordx4 v[168:169], v[186:189], off
	v_or_b32_e32 v150, 48, v138
	v_cmp_gt_i32_e32 vcc, s41, v150
	v_cmp_lt_i32_e64 s[6:7], s50, v150
	s_waitcnt vmcnt(5)
	v_pk_fma_f32 v[192:193], v[98:99], v[208:209], v[192:193]
	v_pk_fma_f32 v[190:191], v[96:97], v[206:207], v[190:191]
	global_store_dwordx4 v[168:169], v[190:193], off offset:64
	s_waitcnt vmcnt(4)
	v_pk_fma_f32 v[196:197], v[78:79], v[212:213], v[196:197]
	v_pk_fma_f32 v[194:195], v[76:77], v[210:211], v[194:195]
	global_store_dwordx4 v[168:169], v[194:197], off offset:512
	s_waitcnt vmcnt(3)
	v_pk_fma_f32 v[200:201], v[74:75], v[216:217], v[200:201]
	v_pk_fma_f32 v[198:199], v[72:73], v[214:215], v[198:199]
	global_store_dwordx4 v[168:169], v[198:201], off offset:576
	s_and_saveexec_b64 s[26:27], s[6:7]
	s_xor_b64 s[6:7], exec, s[26:27]
	v_lshlrev_b64 v[146:147], 13, v[132:133]
	v_mov_b32_e32 v151, v133
	v_lshl_add_u64 v[148:149], s[12:13], 0, v[146:147]
	v_lshlrev_b64 v[146:147], 13, v[150:151]
	s_andn2_saveexec_b64 s[6:7], s[6:7]
	v_ashrrev_i32_e32 v151, 31, v150
	v_lshlrev_b64 v[146:147], 13, v[150:151]
	v_lshl_add_u64 v[148:149], s[10:11], 0, v[146:147]
	s_or_b64 exec, exec, s[6:7]
	v_lshrrev_b32_e32 v132, 2, v132
	v_add_u32_e32 v132, 4, v132
	v_mov_b32_e32 v139, s24
	v_cndmask_b32_e32 v132, v132, v139, vcc
	v_mov_b64_e32 v[150:151], s[14:15]
	v_mad_i64_i32 v[158:159], s[6:7], v132, s48, v[150:151]
	v_lshl_add_u64 v[166:167], v[148:149], 0, v[144:145]
	v_lshl_add_u64 v[158:159], v[158:159], 0, v[144:145]
	global_load_dwordx4 v[186:189], v[166:167], off
	global_load_dwordx4 v[202:205], v[158:159], off
	global_load_dwordx4 v[190:193], v[166:167], off offset:64
	global_load_dwordx4 v[206:209], v[158:159], off offset:64
	global_load_dwordx4 v[194:197], v[166:167], off offset:512
	global_load_dwordx4 v[210:213], v[158:159], off offset:512
	global_load_dwordx4 v[198:201], v[166:167], off offset:576
	global_load_dwordx4 v[214:217], v[158:159], off offset:576
	v_lshl_add_u64 v[146:147], s[10:11], 0, v[146:147]
	v_lshl_add_u64 v[168:169], v[146:147], 0, v[144:145]
	v_cmp_gt_i32_e32 vcc, s51, v138
	v_cmp_lt_i32_e64 s[6:7], s52, v138
	v_add_u32_e32 v132, 0xffffe080, v138
	s_waitcnt vmcnt(6)
	v_pk_fma_f32 v[188:189], v[90:91], v[204:205], v[188:189]
	v_pk_fma_f32 v[186:187], v[88:89], v[202:203], v[186:187]
	global_store_dwordx4 v[168:169], v[186:189], off
	s_waitcnt vmcnt(5)
	v_pk_fma_f32 v[192:193], v[82:83], v[208:209], v[192:193]
	v_pk_fma_f32 v[190:191], v[80:81], v[206:207], v[190:191]
	global_store_dwordx4 v[168:169], v[190:193], off offset:64
	s_waitcnt vmcnt(4)
	v_pk_fma_f32 v[196:197], v[70:71], v[212:213], v[196:197]
	v_pk_fma_f32 v[194:195], v[68:69], v[210:211], v[194:195]
	global_store_dwordx4 v[168:169], v[194:197], off offset:512
	v_add_u32_e32 v146, 0x80, v138
	s_waitcnt vmcnt(3)
	v_pk_fma_f32 v[200:201], v[66:67], v[216:217], v[200:201]
	v_pk_fma_f32 v[198:199], v[64:65], v[214:215], v[198:199]
	global_store_dwordx4 v[168:169], v[198:201], off offset:576
	s_and_saveexec_b64 s[24:25], s[6:7]
	s_xor_b64 s[6:7], exec, s[24:25]
	v_lshlrev_b64 v[148:149], 13, v[132:133]
	v_mov_b32_e32 v147, v133
	v_lshl_add_u64 v[150:151], s[12:13], 0, v[148:149]
	v_lshlrev_b64 v[148:149], 13, v[146:147]
	s_andn2_saveexec_b64 s[6:7], s[6:7]
	v_ashrrev_i32_e32 v147, 31, v146
	v_lshlrev_b64 v[148:149], 13, v[146:147]
	v_lshl_add_u64 v[150:151], s[10:11], 0, v[148:149]
	s_or_b64 exec, exec, s[6:7]
	v_lshrrev_b32_e32 v132, 2, v132
	v_ashrrev_i32_e32 v139, 11, v146
	v_or_b32_e32 v132, 4, v132
	v_cndmask_b32_e32 v132, v132, v139, vcc
	v_mov_b64_e32 v[146:147], s[14:15]
	v_mad_i64_i32 v[146:147], s[6:7], v132, s48, v[146:147]
	v_lshl_add_u64 v[150:151], v[150:151], 0, v[144:145]
	v_lshl_add_u64 v[158:159], v[146:147], 0, v[144:145]
	global_load_dwordx4 v[186:189], v[150:151], off
	global_load_dwordx4 v[202:205], v[158:159], off
	global_load_dwordx4 v[190:193], v[150:151], off offset:64
	global_load_dwordx4 v[206:209], v[158:159], off offset:64
	global_load_dwordx4 v[194:197], v[150:151], off offset:512
	global_load_dwordx4 v[210:213], v[158:159], off offset:512
	global_load_dwordx4 v[198:201], v[150:151], off offset:576
	global_load_dwordx4 v[214:217], v[158:159], off offset:576
	v_lshl_add_u64 v[146:147], s[10:11], 0, v[148:149]
	v_lshl_add_u64 v[170:171], v[146:147], 0, v[144:145]
	v_cmp_gt_i32_e32 vcc, s53, v138
	v_cmp_lt_i32_e64 s[6:7], s54, v138
	v_add_u32_e32 v132, 0xffffe090, v138
	s_waitcnt vmcnt(6)
	v_pk_fma_f32 v[148:149], v[62:63], v[204:205], v[188:189]
	v_pk_fma_f32 v[146:147], v[60:61], v[202:203], v[186:187]
	global_store_dwordx4 v[170:171], v[146:149], off
	s_waitcnt vmcnt(5)
	v_pk_fma_f32 v[192:193], v[58:59], v[208:209], v[192:193]
	v_pk_fma_f32 v[190:191], v[56:57], v[206:207], v[190:191]
	global_store_dwordx4 v[170:171], v[190:193], off offset:64
	s_waitcnt vmcnt(4)
	v_pk_fma_f32 v[196:197], v[46:47], v[212:213], v[196:197]
	v_pk_fma_f32 v[194:195], v[44:45], v[210:211], v[194:195]
	global_store_dwordx4 v[170:171], v[194:197], off offset:512
	v_add_u32_e32 v150, 0x90, v138
	s_waitcnt vmcnt(3)
;     __device__ __forceinline__ void operator()(const Acc& acc, const Unit& u, int wr, int wc, int fr, int fq) const {
;     ...
;         for (int ai = 0; ai < 2; ++ai)
; #pragma unroll
;             for (int m = 0; m < 4; ++m) { const int row = row0 + ai * HALF + m * 16; const int b = bidx_of_row(row);
;                 const float* xr = (row < TP) ? x0p + (size_t)row * DM : x0s + (size_t)(row - TP) * DM; const float* gr = gate + (size_t)b * MODW; float* orow = X1 + (size_t)row * DM;
; #pragma unroll
;                 for (int bj = 0; bj < 2; ++bj)
; #pragma unroll
;                     for (int n = 0; n < 2; ++n) { const int c = col0 + bj * HALF + n * 16; const f32x4 xv = *(const f32x4*)(xr + c), gv = *(const f32x4*)(gr + c);
;                         *(f32x4*)(orow + c) = xv + gv * acc[ai][bj][m][n]; } }
	v_pk_fma_f32 v[200:201], v[38:39], v[216:217], v[200:201]
	v_pk_fma_f32 v[198:199], v[36:37], v[214:215], v[198:199]
	global_store_dwordx4 v[170:171], v[198:201], off offset:576
	s_and_saveexec_b64 s[24:25], s[6:7]
	s_xor_b64 s[6:7], exec, s[24:25]
	v_lshlrev_b64 v[146:147], 13, v[132:133]
	v_mov_b32_e32 v151, v133
	v_lshl_add_u64 v[148:149], s[12:13], 0, v[146:147]
	v_lshlrev_b64 v[146:147], 13, v[150:151]
	s_andn2_saveexec_b64 s[6:7], s[6:7]
	v_ashrrev_i32_e32 v151, 31, v150
	v_lshlrev_b64 v[146:147], 13, v[150:151]
	v_lshl_add_u64 v[148:149], s[10:11], 0, v[146:147]
	s_or_b64 exec, exec, s[6:7]
	v_lshrrev_b32_e32 v132, 2, v132
	v_add_u32_e32 v132, 4, v132
	v_cndmask_b32_e32 v132, v132, v139, vcc
	v_mov_b64_e32 v[150:151], s[14:15]
	v_mad_i64_i32 v[158:159], s[6:7], v132, s48, v[150:151]
	v_lshl_add_u64 v[166:167], v[148:149], 0, v[144:145]
	v_lshl_add_u64 v[158:159], v[158:159], 0, v[144:145]
	global_load_dwordx4 v[186:189], v[166:167], off
	global_load_dwordx4 v[202:205], v[158:159], off
	global_load_dwordx4 v[190:193], v[166:167], off offset:64
	global_load_dwordx4 v[206:209], v[158:159], off offset:64
	global_load_dwordx4 v[194:197], v[166:167], off offset:512
	global_load_dwordx4 v[210:213], v[158:159], off offset:512
	global_load_dwordx4 v[198:201], v[166:167], off offset:576
	global_load_dwordx4 v[214:217], v[158:159], off offset:576
	v_lshl_add_u64 v[146:147], s[10:11], 0, v[146:147]
	v_lshl_add_u64 v[168:169], v[146:147], 0, v[144:145]
	v_cmp_gt_i32_e32 vcc, s55, v138
	v_cmp_lt_i32_e64 s[6:7], s56, v138
	v_add_u32_e32 v132, 0xffffe0a0, v138
	s_waitcnt vmcnt(6)
	v_pk_fma_f32 v[188:189], v[54:55], v[204:205], v[188:189]
	v_pk_fma_f32 v[186:187], v[52:53], v[202:203], v[186:187]
	global_store_dwordx4 v[168:169], v[186:189], off
	v_add_u32_e32 v150, 0xa0, v138
	s_waitcnt vmcnt(5)
	v_pk_fma_f32 v[192:193], v[50:51], v[208:209], v[192:193]
	v_pk_fma_f32 v[190:191], v[48:49], v[206:207], v[190:191]
	global_store_dwordx4 v[168:169], v[190:193], off offset:64
	s_waitcnt vmcnt(4)
	v_pk_fma_f32 v[196:197], v[30:31], v[212:213], v[196:197]
	v_pk_fma_f32 v[194:195], v[28:29], v[210:211], v[194:195]
	global_store_dwordx4 v[168:169], v[194:197], off offset:512
	s_waitcnt vmcnt(3)
	v_pk_fma_f32 v[200:201], v[22:23], v[216:217], v[200:201]
	v_pk_fma_f32 v[198:199], v[20:21], v[214:215], v[198:199]
	global_store_dwordx4 v[168:169], v[198:201], off offset:576
	s_and_saveexec_b64 s[24:25], s[6:7]
	s_xor_b64 s[6:7], exec, s[24:25]
	v_lshlrev_b64 v[146:147], 13, v[132:133]
	v_mov_b32_e32 v151, v133
	v_lshl_add_u64 v[148:149], s[12:13], 0, v[146:147]
	v_lshlrev_b64 v[146:147], 13, v[150:151]
	s_andn2_saveexec_b64 s[6:7], s[6:7]
	v_ashrrev_i32_e32 v151, 31, v150
	v_lshlrev_b64 v[146:147], 13, v[150:151]
	v_lshl_add_u64 v[148:149], s[10:11], 0, v[146:147]
	s_or_b64 exec, exec, s[6:7]
	v_lshrrev_b32_e32 v132, 2, v132
	v_or_b32_e32 v132, 4, v132
	v_cndmask_b32_e32 v132, v132, v139, vcc
	v_mov_b64_e32 v[150:151], s[14:15]
	v_mad_i64_i32 v[158:159], s[6:7], v132, s48, v[150:151]
	v_lshl_add_u64 v[166:167], v[148:149], 0, v[144:145]
	v_lshl_add_u64 v[158:159], v[158:159], 0, v[144:145]
	global_load_dwordx4 v[186:189], v[166:167], off
	global_load_dwordx4 v[202:205], v[158:159], off
	global_load_dwordx4 v[190:193], v[166:167], off offset:64
	global_load_dwordx4 v[206:209], v[158:159], off offset:64
	global_load_dwordx4 v[194:197], v[166:167], off offset:512
	global_load_dwordx4 v[210:213], v[158:159], off offset:512
	global_load_dwordx4 v[198:201], v[166:167], off offset:576
	global_load_dwordx4 v[214:217], v[158:159], off offset:576
	v_lshl_add_u64 v[146:147], s[10:11], 0, v[146:147]
	v_lshl_add_u64 v[168:169], v[146:147], 0, v[144:145]
	v_cmp_gt_i32_e32 vcc, s57, v138
	v_cmp_lt_i32_e64 s[6:7], s58, v138
	v_add_u32_e32 v132, 0xffffe0b0, v138
	s_waitcnt vmcnt(6)
	v_pk_fma_f32 v[188:189], v[42:43], v[204:205], v[188:189]
	v_pk_fma_f32 v[186:187], v[40:41], v[202:203], v[186:187]
	global_store_dwordx4 v[168:169], v[186:189], off
	v_add_u32_e32 v150, 0xb0, v138
	s_waitcnt vmcnt(5)
	v_pk_fma_f32 v[192:193], v[34:35], v[208:209], v[192:193]
	v_pk_fma_f32 v[190:191], v[32:33], v[206:207], v[190:191]
	global_store_dwordx4 v[168:169], v[190:193], off offset:64
	s_waitcnt vmcnt(4)
	v_pk_fma_f32 v[196:197], v[14:15], v[212:213], v[196:197]
	v_pk_fma_f32 v[194:195], v[12:13], v[210:211], v[194:195]
	global_store_dwordx4 v[168:169], v[194:197], off offset:512
	s_waitcnt vmcnt(3)
	v_pk_fma_f32 v[200:201], v[10:11], v[216:217], v[200:201]
	v_pk_fma_f32 v[198:199], v[8:9], v[214:215], v[198:199]
	global_store_dwordx4 v[168:169], v[198:201], off offset:576
	s_and_saveexec_b64 s[24:25], s[6:7]
	s_xor_b64 s[6:7], exec, s[24:25]
	v_lshlrev_b64 v[146:147], 13, v[132:133]
	v_mov_b32_e32 v151, v133
	v_lshl_add_u64 v[148:149], s[12:13], 0, v[146:147]
	v_lshlrev_b64 v[146:147], 13, v[150:151]
	s_andn2_saveexec_b64 s[6:7], s[6:7]
	v_ashrrev_i32_e32 v151, 31, v150
	v_lshlrev_b64 v[146:147], 13, v[150:151]
	v_lshl_add_u64 v[148:149], s[10:11], 0, v[146:147]
	s_or_b64 exec, exec, s[6:7]
	v_lshrrev_b32_e32 v132, 2, v132
	v_add_u32_e32 v132, 4, v132
	v_cndmask_b32_e32 v132, v132, v139, vcc
	v_mov_b64_e32 v[150:151], s[14:15]
	v_mad_i64_i32 v[158:159], s[6:7], v132, s48, v[150:151]
	v_lshl_add_u64 v[166:167], v[148:149], 0, v[144:145]
	v_lshl_add_u64 v[158:159], v[158:159], 0, v[144:145]
	global_load_dwordx4 v[186:189], v[166:167], off
	global_load_dwordx4 v[202:205], v[158:159], off
	global_load_dwordx4 v[190:193], v[166:167], off offset:64
	global_load_dwordx4 v[206:209], v[158:159], off offset:64
	global_load_dwordx4 v[194:197], v[166:167], off offset:512
	global_load_dwordx4 v[210:213], v[158:159], off offset:512
	global_load_dwordx4 v[198:201], v[166:167], off offset:576
	global_load_dwordx4 v[214:217], v[158:159], off offset:576
	v_lshl_add_u64 v[146:147], s[10:11], 0, v[146:147]
	v_lshl_add_u64 v[168:169], v[146:147], 0, v[144:145]
	s_mov_b64 s[6:7], 0
	s_waitcnt vmcnt(6)
	v_pk_fma_f32 v[146:147], v[26:27], v[204:205], v[188:189]
	v_pk_fma_f32 v[144:145], v[24:25], v[202:203], v[186:187]
	global_store_dwordx4 v[168:169], v[144:147], off
	s_waitcnt vmcnt(5)
	v_pk_fma_f32 v[192:193], v[18:19], v[208:209], v[192:193]
	v_pk_fma_f32 v[190:191], v[16:17], v[206:207], v[190:191]
	global_store_dwordx4 v[168:169], v[190:193], off offset:64
	s_waitcnt vmcnt(4)
	v_pk_fma_f32 v[196:197], v[6:7], v[212:213], v[196:197]
	v_pk_fma_f32 v[194:195], v[4:5], v[210:211], v[194:195]
	global_store_dwordx4 v[168:169], v[194:197], off offset:512
	s_waitcnt vmcnt(3)
	v_pk_fma_f32 v[200:201], v[2:3], v[216:217], v[200:201]
	v_pk_fma_f32 v[198:199], v[0:1], v[214:215], v[198:199]
	global_store_dwordx4 v[168:169], v[198:201], off offset:576
